# EpiRes (out-proj, down-proj epilogues): second 128-row half's residual loads issued with the first half's (+0x40000 B) into spare VGPRs, copied by v_mov at the old site, the second half's load waits r
# speedup vs baseline: 1.0156x; 1.0156x over previous
; __device__ __forceinline__ unsigned cvt_pk(float lo, float hi) { unsigned r; asm("v_cvt_pk_bf16_f32 %0, %1, %2" : "=v"(r) : "v"(lo), "v"(hi)); return r; }
;     __device__ __forceinline__ void operator()(AccRef acc, const pg8::Unit& u, int wr, int wc, int, int) const {
;     ...
;                 v4u pw[4][2];
; #pragma unroll
;                 for (int m = 0; m < 4; ++m) { const int row = u.pm * 256 + ai * 128 + wr * 64 + m * 16 + fr;
; #pragma unroll
;                     for (int bj = 0; bj < 2; ++bj) pw[m][bj] = *(const v4u*)(RB + (size_t)row * DM + u.pn * 256 + bj * 128 + wc * 32 + 8 * fq); }
; #pragma unroll
;                 for (int m = 0; m < 4; ++m)
; #pragma unroll
;                     for (int bj = 0; bj < 2; ++bj) { const v4u w = pw[m][bj]; r0[m][bj] = (f32x4){bf_lo(w.x), bf_hi(w.x), bf_lo(w.y), bf_hi(w.y)}; r1[m][bj] = (f32x4){bf_lo(w.z), bf_hi(w.z), bf_lo(w.w), bf_hi(w.w)}; }
;             }
;             asm volatile("" ::: "memory");
; #pragma unroll
;             for (int m = 0; m < 4; ++m) {
;                 const int row = u.pm * 256 + ai * 128 + wr * 64 + m * 16 + fr;
;                 float ss = 0.f;
; #pragma unroll
;                 for (int bj = 0; bj < 2; ++bj) {
;                     const int c0 = u.pn * 256 + bj * 128 + wc * 32 + 8 * fq;
;                     const f32x4 o0 = r0[m][bj] + acc[ai][bj][m][0], o1 = r1[m][bj] + acc[ai][bj][m][1];
;                     v4u w; w.x = cvt_pk(o0[0], o0[1]); w.y = cvt_pk(o0[2], o0[3]); w.z = cvt_pk(o1[0], o1[1]); w.w = cvt_pk(o1[2], o1[3]);
;                     *(v4u*)(HB + (size_t)row * DM + c0) = w;
;                     ss += (o0[0] * o0[0] + o0[1] * o0[1]) + (o0[2] * o0[2] + o0[3] * o0[3]) + (o1[0] * o1[0] + o1[1] * o1[1]) + (o1[2] * o1[2] + o1[3] * o1[3]);
;                 }
;                 if (ssq_off >= 0) { ss += __shfl_xor(ss, 16); ss += __shfl_xor(ss, 32); if (fq == 0) __hip_atomic_fetch_add(ssq + row, ss, __ATOMIC_RELAXED, __HIP_MEMORY_SCOPE_AGENT); }
.LBB0_459:
	s_mov_b64 s[36:37], s[44:45]
	s_mov_b64 s[38:39], s[46:47]
	s_add_u32 s58, s36, 0x7800000
	s_addc_u32 s59, s37, 0
	s_add_u32 s56, s36, 0x22000
	v_mov_b32_e32 v130, v196
	s_addc_u32 s57, s37, 0
	s_lshl_b32 s15, s76, 8
	s_lshl_b32 s38, s66, 8
	s_add_i32 s15, s15, s35
	v_ashrrev_i32_e32 v128, 1, v130
	s_ashr_i32 s39, s38, 31
	v_and_or_b32 v166, v130, 15, s15
	v_and_b32_e32 v128, -8, v128
	s_or_b32 s15, s38, s28
	s_lshl_b64 s[38:39], s[38:39], 1
	v_add_u32_e32 v164, s15, v128
	s_add_u32 s15, s36, s38
	s_addc_u32 s31, s37, s39
	s_add_u32 s36, s15, s70
	s_addc_u32 s37, s31, 0
	v_ashrrev_i32_e32 v129, 31, v128
	v_lshl_add_u64 v[128:129], v[128:129], 1, s[36:37]
	s_mov_b64 s[36:37], 0x3600000
	v_ashrrev_i32_e32 v167, 31, v166
	v_lshl_add_u64 v[168:169], v[128:129], 0, s[36:37]
	v_lshlrev_b64 v[200:201], 11, v[166:167]
	v_lshl_add_u64 v[128:129], v[168:169], 0, v[200:201]
	s_mov_b64 s[78:79], 0x40000
	v_lshl_add_u64 v[244:245], v[128:129], 0, s[78:79]
	global_load_dwordx4 v[188:191], v[128:129], off
	global_load_dwordx4 v[192:195], v[128:129], off offset:256
	global_load_dwordx4 v[212:215], v[244:245], off
	global_load_dwordx4 v[216:219], v[244:245], off offset:256
	v_or_b32_e32 v176, 16, v166
	v_ashrrev_i32_e32 v177, 31, v176
	v_or_b32_e32 v172, 32, v166
	v_lshlrev_b64 v[180:181], 11, v[176:177]
	v_ashrrev_i32_e32 v173, 31, v172
	v_or_b32_e32 v170, 48, v166
	v_lshl_add_u64 v[128:129], v[168:169], 0, v[180:181]
	v_lshlrev_b64 v[178:179], 11, v[172:173]
	v_ashrrev_i32_e32 v171, 31, v170
	v_lshl_add_u64 v[244:245], v[128:129], 0, s[78:79]
	global_load_dwordx4 v[148:151], v[128:129], off
	global_load_dwordx4 v[144:147], v[128:129], off offset:256
	global_load_dwordx4 v[220:223], v[244:245], off
	global_load_dwordx4 v[224:227], v[244:245], off offset:256
	v_lshl_add_u64 v[128:129], v[168:169], 0, v[178:179]
	v_lshlrev_b64 v[174:175], 11, v[170:171]
	v_lshl_add_u64 v[244:245], v[128:129], 0, s[78:79]
	global_load_dwordx4 v[140:143], v[128:129], off
	global_load_dwordx4 v[136:139], v[128:129], off offset:256
	global_load_dwordx4 v[228:231], v[244:245], off
	global_load_dwordx4 v[232:235], v[244:245], off offset:256
	v_lshl_add_u64 v[128:129], v[168:169], 0, v[174:175]
	v_cmp_gt_u32_e32 vcc, 16, v130
	v_lshl_add_u64 v[244:245], v[128:129], 0, s[78:79]
	global_load_dwordx4 v[132:135], v[128:129], off
	s_nop 0
	global_load_dwordx4 v[128:131], v[128:129], off offset:256
	global_load_dwordx4 v[236:239], v[244:245], off
	global_load_dwordx4 v[240:243], v[244:245], off offset:256
	v_ashrrev_i32_e32 v165, 31, v164
	v_lshl_add_u64 v[200:201], s[58:59], 0, v[200:201]
	v_lshl_add_u64 v[200:201], v[164:165], 1, v[200:201]
	s_waitcnt vmcnt(0)
	v_lshlrev_b32_e32 v202, 16, v188
	v_and_b32_e32 v203, 0xffff0000, v188
	v_lshlrev_b32_e32 v188, 16, v189
	v_and_b32_e32 v189, 0xffff0000, v189
	v_lshlrev_b32_e32 v204, 16, v190
	v_and_b32_e32 v205, 0xffff0000, v190
	v_lshlrev_b32_e32 v190, 16, v191
	v_and_b32_e32 v191, 0xffff0000, v191
	v_lshlrev_b32_e32 v206, 16, v192
	v_and_b32_e32 v207, 0xffff0000, v192
	v_lshlrev_b32_e32 v192, 16, v193
	v_and_b32_e32 v193, 0xffff0000, v193
	v_lshlrev_b32_e32 v208, 16, v194
	v_and_b32_e32 v209, 0xffff0000, v194
	v_lshlrev_b32_e32 v194, 16, v195
	v_and_b32_e32 v195, 0xffff0000, v195
	v_pk_add_f32 v[126:127], v[126:127], v[188:189]
	v_pk_add_f32 v[124:125], v[124:125], v[202:203]
	v_pk_add_f32 v[188:189], v[122:123], v[190:191]
	v_pk_add_f32 v[190:191], v[120:121], v[204:205]
	v_cvt_pk_bf16_f32 v120, v124, v125
	v_cvt_pk_bf16_f32 v121, v126, v127
	v_cvt_pk_bf16_f32 v123, v188, v189
	v_pk_add_f32 v[118:119], v[118:119], v[192:193]
	v_cvt_pk_bf16_f32 v122, v190, v191
	global_store_dwordx4 v[200:201], v[120:123], off
	v_pk_add_f32 v[116:117], v[116:117], v[206:207]
	s_nop 0
	v_pk_add_f32 v[120:121], v[114:115], v[194:195]
	v_pk_add_f32 v[122:123], v[112:113], v[208:209]
	v_cvt_pk_bf16_f32 v113, v118, v119
	v_cvt_pk_bf16_f32 v112, v116, v117
	v_cvt_pk_bf16_f32 v115, v120, v121
	s_nop 0
	v_cvt_pk_bf16_f32 v114, v122, v123
	global_store_dwordx4 v[200:201], v[112:115], off offset:256
	s_nop 1
	v_mul_f32_e32 v113, v125, v125
	v_mul_f32_e32 v114, v127, v127
	v_fmac_f32_e32 v113, v124, v124
	v_fmac_f32_e32 v114, v126, v126
	v_add_f32_e32 v113, v113, v114
	v_mul_f32_e32 v114, v191, v191
	v_fmac_f32_e32 v114, v190, v190
	v_add_f32_e32 v113, v114, v113
	v_mul_f32_e32 v114, v117, v117
	v_mul_f32_e32 v115, v119, v119
	v_mul_f32_e32 v112, v189, v189
	v_fmac_f32_e32 v114, v116, v116
	v_fmac_f32_e32 v115, v118, v118
	v_fmac_f32_e32 v112, v188, v188
	v_add_f32_e32 v114, v114, v115
	v_mul_f32_e32 v115, v123, v123
	v_add_f32_e32 v112, v112, v113
	v_mul_f32_e32 v113, v121, v121
	v_fmac_f32_e32 v115, v122, v122
	v_fmac_f32_e32 v113, v120, v120
	v_add_f32_e32 v114, v115, v114
	v_add_f32_e32 v113, v113, v114
	v_add_f32_e32 v112, v112, v113
	ds_bpermute_b32 v113, v197, v112
	s_waitcnt lgkmcnt(0)
	v_add_f32_e32 v112, v112, v113
	ds_bpermute_b32 v113, v198, v112
	s_and_saveexec_b64 s[66:67], vcc
	s_cbranch_execz .LBB0_461
	s_waitcnt lgkmcnt(0)
	v_add_f32_e32 v114, v112, v113
	v_lshl_add_u64 v[112:113], v[166:167], 2, s[56:57]
	global_atomic_add_f32 v[112:113], v114, off

; __device__ __forceinline__ unsigned cvt_pk(float lo, float hi) { unsigned r; asm("v_cvt_pk_bf16_f32 %0, %1, %2" : "=v"(r) : "v"(lo), "v"(hi)); return r; }
;     __device__ __forceinline__ void operator()(AccRef acc, const pg8::Unit& u, int wr, int wc, int, int) const {
;     ...
;                 for (int m = 0; m < 4; ++m) { const int row = u.pm * 256 + ai * 128 + wr * 64 + m * 16 + fr;
; #pragma unroll
;                     for (int bj = 0; bj < 2; ++bj) pw[m][bj] = *(const v4u*)(RB + (size_t)row * DM + u.pn * 256 + bj * 128 + wc * 32 + 8 * fq); }
; #pragma unroll
;                 for (int m = 0; m < 4; ++m)
; #pragma unroll
;                     for (int bj = 0; bj < 2; ++bj) { const v4u w = pw[m][bj]; r0[m][bj] = (f32x4){bf_lo(w.x), bf_hi(w.x), bf_lo(w.y), bf_hi(w.y)}; r1[m][bj] = (f32x4){bf_lo(w.z), bf_hi(w.z), bf_lo(w.w), bf_hi(w.w)}; }
;             }
;             asm volatile("" ::: "memory");
; #pragma unroll
;             for (int m = 0; m < 4; ++m) {
;                 const int row = u.pm * 256 + ai * 128 + wr * 64 + m * 16 + fr;
;                 float ss = 0.f;
; #pragma unroll
;                 for (int bj = 0; bj < 2; ++bj) {
;                     const int c0 = u.pn * 256 + bj * 128 + wc * 32 + 8 * fq;
;                     const f32x4 o0 = r0[m][bj] + acc[ai][bj][m][0], o1 = r1[m][bj] + acc[ai][bj][m][1];
;                     v4u w; w.x = cvt_pk(o0[0], o0[1]); w.y = cvt_pk(o0[2], o0[3]); w.z = cvt_pk(o1[0], o1[1]); w.w = cvt_pk(o1[2], o1[3]);
;                     *(v4u*)(HB + (size_t)row * DM + c0) = w;
;                     ss += (o0[0] * o0[0] + o0[1] * o0[1]) + (o0[2] * o0[2] + o0[3] * o0[3]) + (o1[0] * o1[0] + o1[1] * o1[1]) + (o1[2] * o1[2] + o1[3] * o1[3]);
;                 }
;                 if (ssq_off >= 0) { ss += __shfl_xor(ss, 16); ss += __shfl_xor(ss, 32); if (fq == 0) __hip_atomic_fetch_add(ssq + row, ss, __ATOMIC_RELAXED, __HIP_MEMORY_SCOPE_AGENT); }
.LBB0_467:
	s_or_b64 exec, exec, s[66:67]
	v_add_u32_e32 v98, 0x80, v166
	v_ashrrev_i32_e32 v99, 31, v98
	v_lshlrev_b64 v[110:111], 11, v[98:99]
	s_waitcnt lgkmcnt(0)
	v_lshl_add_u64 v[64:65], v[168:169], 0, v[110:111]
	v_mov_b64_e32 v[102:103], v[212:213]
	v_mov_b64_e32 v[104:105], v[214:215]
	v_mov_b64_e32 v[106:107], v[216:217]
	v_mov_b64_e32 v[108:109], v[218:219]
	v_add_u32_e32 v94, 0x90, v166
	v_add_u32_e32 v92, 0xa0, v166
	v_add_u32_e32 v88, 0xb0, v166
	v_ashrrev_i32_e32 v95, 31, v94
	v_ashrrev_i32_e32 v93, 31, v92
	v_ashrrev_i32_e32 v89, 31, v88
	v_lshlrev_b64 v[100:101], 11, v[94:95]
	v_lshlrev_b64 v[96:97], 11, v[92:93]
	v_lshlrev_b64 v[90:91], 11, v[88:89]
	v_lshl_add_u64 v[64:65], v[168:169], 0, v[100:101]
	v_lshl_add_u64 v[66:67], v[168:169], 0, v[96:97]
	v_lshl_add_u64 v[112:113], v[168:169], 0, v[90:91]
	v_mov_b64_e32 v[84:85], v[220:221]
	v_mov_b64_e32 v[86:87], v[222:223]
	v_mov_b64_e32 v[80:81], v[224:225]
	v_mov_b64_e32 v[82:83], v[226:227]
	v_mov_b64_e32 v[76:77], v[228:229]
	v_mov_b64_e32 v[78:79], v[230:231]
	v_mov_b64_e32 v[72:73], v[232:233]
	v_mov_b64_e32 v[74:75], v[234:235]
	v_mov_b64_e32 v[68:69], v[236:237]
	v_mov_b64_e32 v[70:71], v[238:239]
	s_nop 0
	v_mov_b64_e32 v[64:65], v[240:241]
	v_mov_b64_e32 v[66:67], v[242:243]
	v_lshl_add_u64 v[110:111], s[58:59], 0, v[110:111]
	v_lshlrev_b32_e32 v112, 16, v102
	v_and_b32_e32 v113, 0xffff0000, v102
	v_lshlrev_b32_e32 v102, 16, v103
	v_and_b32_e32 v103, 0xffff0000, v103
	v_lshlrev_b32_e32 v116, 16, v106
	v_and_b32_e32 v117, 0xffff0000, v106
	v_lshlrev_b32_e32 v106, 16, v107
	v_and_b32_e32 v107, 0xffff0000, v107
	v_lshlrev_b32_e32 v114, 16, v104
	v_and_b32_e32 v115, 0xffff0000, v104
	v_lshlrev_b32_e32 v104, 16, v105
	v_and_b32_e32 v105, 0xffff0000, v105
	v_lshlrev_b32_e32 v118, 16, v108
	v_and_b32_e32 v119, 0xffff0000, v108
	v_lshlrev_b32_e32 v108, 16, v109
	v_and_b32_e32 v109, 0xffff0000, v109
	v_pk_add_f32 v[62:63], v[62:63], v[102:103]
	v_pk_add_f32 v[60:61], v[60:61], v[112:113]
	v_pk_add_f32 v[54:55], v[54:55], v[106:107]
	v_pk_add_f32 v[52:53], v[52:53], v[116:117]
	v_pk_add_f32 v[58:59], v[58:59], v[104:105]
	v_pk_add_f32 v[56:57], v[56:57], v[114:115]
	v_pk_add_f32 v[102:103], v[50:51], v[108:109]
	v_pk_add_f32 v[104:105], v[48:49], v[118:119]
	v_cvt_pk_bf16_f32 v48, v60, v61
	v_cvt_pk_bf16_f32 v49, v62, v63
	v_mul_f32_e32 v61, v61, v61
	v_mul_f32_e32 v63, v63, v63
	v_mul_f32_e32 v107, v53, v53
	v_mul_f32_e32 v108, v55, v55
	v_cvt_pk_bf16_f32 v50, v56, v57
	v_mul_f32_e32 v57, v57, v57
	v_mul_f32_e32 v109, v105, v105
	v_fmac_f32_e32 v61, v60, v60
	v_fmac_f32_e32 v63, v62, v62
	v_fmac_f32_e32 v107, v52, v52
	v_fmac_f32_e32 v108, v54, v54
	v_mul_f32_e32 v51, v59, v59
	v_mul_f32_e32 v106, v103, v103
	v_fmac_f32_e32 v57, v56, v56
	v_fmac_f32_e32 v109, v104, v104
	v_add_f32_e32 v56, v61, v63
	v_add_f32_e32 v60, v107, v108
	v_fmac_f32_e32 v51, v58, v58
	v_fmac_f32_e32 v106, v102, v102
	v_add_f32_e32 v56, v57, v56
	v_add_f32_e32 v57, v109, v60
	v_add_f32_e32 v51, v51, v56
	v_add_f32_e32 v56, v106, v57
	v_add_f32_e32 v60, v51, v56
	ds_bpermute_b32 v61, v197, v60
	v_lshl_add_u64 v[56:57], v[164:165], 1, v[110:111]
	v_cvt_pk_bf16_f32 v51, v58, v59
	global_store_dwordx4 v[56:57], v[48:51], off
	s_waitcnt lgkmcnt(0)
	s_nop 0
	v_add_f32_e32 v48, v60, v61
	ds_bpermute_b32 v49, v198, v48
	v_cvt_pk_bf16_f32 v50, v52, v53
	v_cvt_pk_bf16_f32 v51, v54, v55
	v_cvt_pk_bf16_f32 v52, v104, v105
	v_cvt_pk_bf16_f32 v53, v102, v103
	global_store_dwordx4 v[56:57], v[50:53], off offset:256
	s_and_saveexec_b64 s[66:67], vcc
	s_cbranch_execz .LBB0_469
	s_waitcnt lgkmcnt(0)
	v_add_f32_e32 v50, v48, v49
	v_lshl_add_u64 v[48:49], v[98:99], 2, s[56:57]
	global_atomic_add_f32 v[48:49], v50, off
.LBB0_469:
	s_or_b64 exec, exec, s[66:67]
	v_lshlrev_b32_e32 v48, 16, v84
	s_waitcnt lgkmcnt(0)
	v_and_b32_e32 v49, 0xffff0000, v84
	v_lshlrev_b32_e32 v50, 16, v85
	v_and_b32_e32 v51, 0xffff0000, v85
	v_lshlrev_b32_e32 v52, 16, v86
	v_and_b32_e32 v53, 0xffff0000, v86
	v_lshlrev_b32_e32 v54, 16, v87
	v_and_b32_e32 v55, 0xffff0000, v87
	v_lshlrev_b32_e32 v60, 16, v82
	v_and_b32_e32 v61, 0xffff0000, v82
	v_lshlrev_b32_e32 v62, 16, v83
	v_and_b32_e32 v63, 0xffff0000, v83
	v_pk_add_f32 v[46:47], v[46:47], v[50:51]
	v_pk_add_f32 v[44:45], v[44:45], v[48:49]
	v_pk_add_f32 v[48:49], v[42:43], v[54:55]
	v_pk_add_f32 v[50:51], v[40:41], v[52:53]
	v_pk_add_f32 v[52:53], v[34:35], v[62:63]
	v_pk_add_f32 v[54:55], v[32:33], v[60:61]
	v_mul_f32_e32 v33, v45, v45
	v_mul_f32_e32 v34, v47, v47
	v_fmac_f32_e32 v33, v44, v44
	v_fmac_f32_e32 v34, v46, v46
	v_lshlrev_b32_e32 v56, 16, v80
	v_and_b32_e32 v57, 0xffff0000, v80
	v_lshlrev_b32_e32 v58, 16, v81
	v_and_b32_e32 v59, 0xffff0000, v81
	v_add_f32_e32 v33, v33, v34
	v_mul_f32_e32 v34, v51, v51
	v_pk_add_f32 v[38:39], v[38:39], v[58:59]
	v_pk_add_f32 v[36:37], v[36:37], v[56:57]
	v_fmac_f32_e32 v34, v50, v50
	v_add_f32_e32 v33, v34, v33
	v_mul_f32_e32 v34, v37, v37
	v_mul_f32_e32 v35, v39, v39
	v_mul_f32_e32 v32, v49, v49
	v_fmac_f32_e32 v34, v36, v36
	v_fmac_f32_e32 v35, v38, v38
	v_fmac_f32_e32 v32, v48, v48
	v_add_f32_e32 v34, v34, v35
	v_mul_f32_e32 v35, v55, v55
	v_add_f32_e32 v32, v32, v33
	v_mul_f32_e32 v33, v53, v53
	v_fmac_f32_e32 v35, v54, v54
	v_fmac_f32_e32 v33, v52, v52
	v_add_f32_e32 v34, v35, v34
	v_add_f32_e32 v33, v33, v34
	v_add_f32_e32 v32, v32, v33
	ds_bpermute_b32 v33, v197, v32
	v_lshl_add_u64 v[80:81], s[58:59], 0, v[100:101]
	v_cvt_pk_bf16_f32 v40, v44, v45
	v_lshl_add_u64 v[44:45], v[164:165], 1, v[80:81]
	v_cvt_pk_bf16_f32 v41, v46, v47
	s_waitcnt lgkmcnt(0)
	v_add_f32_e32 v32, v32, v33
	ds_bpermute_b32 v33, v198, v32
	v_cvt_pk_bf16_f32 v42, v50, v51
	v_cvt_pk_bf16_f32 v43, v48, v49
	global_store_dwordx4 v[44:45], v[40:43], off
	v_cvt_pk_bf16_f32 v34, v36, v37
	v_cvt_pk_bf16_f32 v35, v38, v39
	v_cvt_pk_bf16_f32 v36, v54, v55
	v_cvt_pk_bf16_f32 v37, v52, v53
	global_store_dwordx4 v[44:45], v[34:37], off offset:256
	s_and_saveexec_b64 s[66:67], vcc
	s_cbranch_execz .LBB0_471
	s_waitcnt lgkmcnt(0)
	v_add_f32_e32 v34, v32, v33
	v_lshl_add_u64 v[32:33], v[94:95], 2, s[56:57]
	global_atomic_add_f32 v[32:33], v34, off
; __device__ __forceinline__ unsigned cvt_pk(float lo, float hi) { unsigned r; asm("v_cvt_pk_bf16_f32 %0, %1, %2" : "=v"(r) : "v"(lo), "v"(hi)); return r; }
;     __device__ __forceinline__ void operator()(AccRef acc, const pg8::Unit& u, int wr, int wc, int, int) const {
;     ...
;             for (int m = 0; m < 4; ++m) {
;                 const int row = u.pm * 256 + ai * 128 + wr * 64 + m * 16 + fr;
;                 float ss = 0.f;
; #pragma unroll
;                 for (int bj = 0; bj < 2; ++bj) {
;                     const int c0 = u.pn * 256 + bj * 128 + wc * 32 + 8 * fq;
;                     const f32x4 o0 = r0[m][bj] + acc[ai][bj][m][0], o1 = r1[m][bj] + acc[ai][bj][m][1];
;                     v4u w; w.x = cvt_pk(o0[0], o0[1]); w.y = cvt_pk(o0[2], o0[3]); w.z = cvt_pk(o1[0], o1[1]); w.w = cvt_pk(o1[2], o1[3]);
;                     *(v4u*)(HB + (size_t)row * DM + c0) = w;
;                     ss += (o0[0] * o0[0] + o0[1] * o0[1]) + (o0[2] * o0[2] + o0[3] * o0[3]) + (o1[0] * o1[0] + o1[1] * o1[1]) + (o1[2] * o1[2] + o1[3] * o1[3]);
;                 }
;                 if (ssq_off >= 0) { ss += __shfl_xor(ss, 16); ss += __shfl_xor(ss, 32); if (fq == 0) __hip_atomic_fetch_add(ssq + row, ss, __ATOMIC_RELAXED, __HIP_MEMORY_SCOPE_AGENT); }
.LBB0_471:
	s_or_b64 exec, exec, s[66:67]
	v_lshlrev_b32_e32 v32, 16, v76
	s_waitcnt lgkmcnt(0)
	v_and_b32_e32 v33, 0xffff0000, v76
	v_lshlrev_b32_e32 v34, 16, v77
	v_and_b32_e32 v35, 0xffff0000, v77
	v_lshlrev_b32_e32 v36, 16, v78
	v_and_b32_e32 v37, 0xffff0000, v78
	v_lshlrev_b32_e32 v38, 16, v79
	v_and_b32_e32 v39, 0xffff0000, v79
	v_lshlrev_b32_e32 v44, 16, v74
	v_and_b32_e32 v45, 0xffff0000, v74
	v_lshlrev_b32_e32 v46, 16, v75
	v_and_b32_e32 v47, 0xffff0000, v75
	v_pk_add_f32 v[30:31], v[30:31], v[34:35]
	v_pk_add_f32 v[28:29], v[28:29], v[32:33]
	v_pk_add_f32 v[32:33], v[26:27], v[38:39]
	v_pk_add_f32 v[34:35], v[24:25], v[36:37]
	v_pk_add_f32 v[36:37], v[18:19], v[46:47]
	v_pk_add_f32 v[38:39], v[16:17], v[44:45]
	v_mul_f32_e32 v17, v29, v29
	v_mul_f32_e32 v18, v31, v31
	v_fmac_f32_e32 v17, v28, v28
	v_fmac_f32_e32 v18, v30, v30
	v_lshlrev_b32_e32 v40, 16, v72
	v_and_b32_e32 v41, 0xffff0000, v72
	v_lshlrev_b32_e32 v42, 16, v73
	v_and_b32_e32 v43, 0xffff0000, v73
	v_add_f32_e32 v17, v17, v18
	v_mul_f32_e32 v18, v35, v35
	v_pk_add_f32 v[22:23], v[22:23], v[42:43]
	v_pk_add_f32 v[20:21], v[20:21], v[40:41]
	v_fmac_f32_e32 v18, v34, v34
	v_add_f32_e32 v17, v18, v17
	v_mul_f32_e32 v18, v21, v21
	v_mul_f32_e32 v19, v23, v23
	v_mul_f32_e32 v16, v33, v33
	v_fmac_f32_e32 v18, v20, v20
	v_fmac_f32_e32 v19, v22, v22
	v_fmac_f32_e32 v16, v32, v32
	v_add_f32_e32 v18, v18, v19
	v_mul_f32_e32 v19, v39, v39
	v_add_f32_e32 v16, v16, v17
	v_mul_f32_e32 v17, v37, v37
	v_fmac_f32_e32 v19, v38, v38
	v_fmac_f32_e32 v17, v36, v36
	v_add_f32_e32 v18, v19, v18
	v_add_f32_e32 v17, v17, v18
	v_add_f32_e32 v16, v16, v17
	ds_bpermute_b32 v17, v197, v16
	v_lshl_add_u64 v[48:49], s[58:59], 0, v[96:97]
	v_cvt_pk_bf16_f32 v24, v28, v29
	v_lshl_add_u64 v[28:29], v[164:165], 1, v[48:49]
	v_cvt_pk_bf16_f32 v25, v30, v31
	s_waitcnt lgkmcnt(0)
	v_add_f32_e32 v16, v16, v17
	ds_bpermute_b32 v17, v198, v16
	v_cvt_pk_bf16_f32 v26, v34, v35
	v_cvt_pk_bf16_f32 v27, v32, v33
	global_store_dwordx4 v[28:29], v[24:27], off
	v_cvt_pk_bf16_f32 v18, v20, v21
	v_cvt_pk_bf16_f32 v19, v22, v23
	v_cvt_pk_bf16_f32 v20, v38, v39
	v_cvt_pk_bf16_f32 v21, v36, v37
	global_store_dwordx4 v[28:29], v[18:21], off offset:256
	s_and_saveexec_b64 s[66:67], vcc
	s_cbranch_execz .LBB0_473
	s_waitcnt lgkmcnt(0)
	v_add_f32_e32 v18, v16, v17
	v_lshl_add_u64 v[16:17], v[92:93], 2, s[56:57]
	global_atomic_add_f32 v[16:17], v18, off
.LBB0_473:
	s_or_b64 exec, exec, s[66:67]
	v_lshlrev_b32_e32 v16, 16, v68
	s_waitcnt lgkmcnt(0)
	v_and_b32_e32 v17, 0xffff0000, v68
	v_lshlrev_b32_e32 v18, 16, v69
	v_and_b32_e32 v19, 0xffff0000, v69
	v_lshlrev_b32_e32 v20, 16, v70
	v_and_b32_e32 v21, 0xffff0000, v70
	v_lshlrev_b32_e32 v22, 16, v71
	v_and_b32_e32 v23, 0xffff0000, v71
	v_lshlrev_b32_e32 v28, 16, v66
	v_and_b32_e32 v29, 0xffff0000, v66
	v_lshlrev_b32_e32 v30, 16, v67
	v_and_b32_e32 v31, 0xffff0000, v67
	v_pk_add_f32 v[14:15], v[14:15], v[18:19]
	v_pk_add_f32 v[12:13], v[12:13], v[16:17]
	v_pk_add_f32 v[16:17], v[10:11], v[22:23]
	v_pk_add_f32 v[18:19], v[8:9], v[20:21]
	v_pk_add_f32 v[20:21], v[2:3], v[30:31]
	v_pk_add_f32 v[22:23], v[0:1], v[28:29]
	v_mul_f32_e32 v1, v13, v13
	v_mul_f32_e32 v2, v15, v15
	v_fmac_f32_e32 v1, v12, v12
	v_fmac_f32_e32 v2, v14, v14
	v_lshlrev_b32_e32 v24, 16, v64
	v_and_b32_e32 v25, 0xffff0000, v64
	v_lshlrev_b32_e32 v26, 16, v65
	v_and_b32_e32 v27, 0xffff0000, v65
	v_add_f32_e32 v1, v1, v2
	v_mul_f32_e32 v2, v19, v19
	v_pk_add_f32 v[6:7], v[6:7], v[26:27]
	v_pk_add_f32 v[4:5], v[4:5], v[24:25]
	v_fmac_f32_e32 v2, v18, v18
	v_add_f32_e32 v1, v2, v1
	v_mul_f32_e32 v2, v5, v5
	v_mul_f32_e32 v3, v7, v7
	v_mul_f32_e32 v0, v17, v17
	v_fmac_f32_e32 v2, v4, v4
	v_fmac_f32_e32 v3, v6, v6
	v_fmac_f32_e32 v0, v16, v16
	v_add_f32_e32 v2, v2, v3
	v_mul_f32_e32 v3, v23, v23
	v_add_f32_e32 v0, v0, v1
	v_mul_f32_e32 v1, v21, v21
	v_fmac_f32_e32 v3, v22, v22
	v_fmac_f32_e32 v1, v20, v20
	v_add_f32_e32 v2, v3, v2
	v_add_f32_e32 v1, v1, v2
	v_add_f32_e32 v0, v0, v1
	ds_bpermute_b32 v1, v197, v0
	v_lshl_add_u64 v[32:33], s[58:59], 0, v[90:91]
	v_cvt_pk_bf16_f32 v8, v12, v13
	v_lshl_add_u64 v[12:13], v[164:165], 1, v[32:33]
	v_cvt_pk_bf16_f32 v9, v14, v15
	s_waitcnt lgkmcnt(0)
	v_add_f32_e32 v0, v0, v1
	ds_bpermute_b32 v1, v198, v0
	v_cvt_pk_bf16_f32 v10, v18, v19
	v_cvt_pk_bf16_f32 v11, v16, v17
	global_store_dwordx4 v[12:13], v[8:11], off
	v_cvt_pk_bf16_f32 v2, v4, v5
	v_cvt_pk_bf16_f32 v3, v6, v7
	v_cvt_pk_bf16_f32 v4, v22, v23
	v_cvt_pk_bf16_f32 v5, v20, v21
	global_store_dwordx4 v[12:13], v[2:5], off offset:256
	s_and_saveexec_b64 s[58:59], vcc
	s_cbranch_execz .LBB0_475
	s_waitcnt lgkmcnt(0)
	v_add_f32_e32 v2, v0, v1
	v_lshl_add_u64 v[0:1], v[88:89], 2, s[56:57]
	global_atomic_add_f32 v[0:1], v2, off

; __device__ __forceinline__ unsigned cvt_pk(float lo, float hi) { unsigned r; asm("v_cvt_pk_bf16_f32 %0, %1, %2" : "=v"(r) : "v"(lo), "v"(hi)); return r; }
;     __device__ __forceinline__ void operator()(AccRef acc, const pg8::Unit& u, int wr, int wc, int, int) const {
;     ...
;                 for (int m = 0; m < 4; ++m) { const int row = u.pm * 256 + ai * 128 + wr * 64 + m * 16 + fr;
; #pragma unroll
;                     for (int bj = 0; bj < 2; ++bj) pw[m][bj] = *(const v4u*)(RB + (size_t)row * DM + u.pn * 256 + bj * 128 + wc * 32 + 8 * fq); }
; #pragma unroll
;                 for (int m = 0; m < 4; ++m)
; #pragma unroll
;                     for (int bj = 0; bj < 2; ++bj) { const v4u w = pw[m][bj]; r0[m][bj] = (f32x4){bf_lo(w.x), bf_hi(w.x), bf_lo(w.y), bf_hi(w.y)}; r1[m][bj] = (f32x4){bf_lo(w.z), bf_hi(w.z), bf_lo(w.w), bf_hi(w.w)}; }
;             }
;             asm volatile("" ::: "memory");
; #pragma unroll
;             for (int m = 0; m < 4; ++m) {
;                 const int row = u.pm * 256 + ai * 128 + wr * 64 + m * 16 + fr;
;                 float ss = 0.f;
; #pragma unroll
;                 for (int bj = 0; bj < 2; ++bj) {
;                     const int c0 = u.pn * 256 + bj * 128 + wc * 32 + 8 * fq;
;                     const f32x4 o0 = r0[m][bj] + acc[ai][bj][m][0], o1 = r1[m][bj] + acc[ai][bj][m][1];
;                     v4u w; w.x = cvt_pk(o0[0], o0[1]); w.y = cvt_pk(o0[2], o0[3]); w.z = cvt_pk(o1[0], o1[1]); w.w = cvt_pk(o1[2], o1[3]);
;                     *(v4u*)(HB + (size_t)row * DM + c0) = w;
.Lp5a_epi:
	s_mov_b64 s[30:31], s[44:45]
	s_mov_b64 s[42:43], s[46:47]
	s_add_u32 s30, s30, 0x7800000
	v_mov_b32_e32 v141, v196
	s_addc_u32 s31, s31, 0
	s_lshl_b32 s42, s68, 8
	s_add_i32 s42, s42, s35
	v_and_or_b32 v140, v141, 15, s42
	s_lshl_b32 s42, s67, 8
	v_ashrrev_i32_e32 v141, 1, v141
	v_and_b32_e32 v142, -8, v141
	s_or_b32 s43, s42, s28
	v_add_u32_e32 v186, s43, v142
	s_ashr_i32 s43, s42, 31
	s_lshl_b64 s[42:43], s[42:43], 1
	s_add_u32 s42, s30, s42
	s_addc_u32 s43, s31, s43
	s_add_u32 s42, s42, s48
	s_addc_u32 s43, s43, 0
	v_ashrrev_i32_e32 v143, 31, v142
	v_ashrrev_i32_e32 v141, 31, v140
	v_lshl_add_u64 v[142:143], v[142:143], 1, s[42:43]
	v_lshlrev_b64 v[188:189], 11, v[140:141]
	v_lshl_add_u64 v[144:145], v[142:143], 0, v[188:189]
	s_mov_b64 s[54:55], 0x40000
	v_lshl_add_u64 v[246:247], v[144:145], 0, s[54:55]
	global_load_dwordx4 v[146:149], v[144:145], off
	global_load_dwordx4 v[158:161], v[144:145], off offset:256
	global_load_dwordx4 v[230:233], v[246:247], off
	global_load_dwordx4 v[234:237], v[246:247], off offset:256
	v_or_b32_e32 v144, 16, v140
	v_ashrrev_i32_e32 v145, 31, v144
	v_lshlrev_b64 v[190:191], 11, v[144:145]
	v_lshl_add_u64 v[144:145], v[142:143], 0, v[190:191]
	v_lshl_add_u64 v[246:247], v[144:145], 0, s[54:55]
	global_load_dwordx4 v[162:165], v[144:145], off
	global_load_dwordx4 v[166:169], v[144:145], off offset:256
	global_load_dwordx4 v[238:241], v[246:247], off
	global_load_dwordx4 v[242:245], v[246:247], off offset:256
	v_or_b32_e32 v144, 32, v140
	v_ashrrev_i32_e32 v145, 31, v144
	v_lshlrev_b64 v[192:193], 11, v[144:145]
	v_lshl_add_u64 v[144:145], v[142:143], 0, v[192:193]
	global_load_dwordx4 v[170:173], v[144:145], off
	global_load_dwordx4 v[174:177], v[144:145], off offset:256
	v_or_b32_e32 v144, 48, v140
	v_ashrrev_i32_e32 v145, 31, v144
	v_lshlrev_b64 v[144:145], 11, v[144:145]
	v_lshl_add_u64 v[150:151], v[142:143], 0, v[144:145]
	global_load_dwordx4 v[178:181], v[150:151], off
	global_load_dwordx4 v[182:185], v[150:151], off offset:256
	v_ashrrev_i32_e32 v187, 31, v186
	s_and_b64 vcc, exec, s[6:7]
	s_waitcnt vmcnt(0)
	v_lshlrev_b32_e32 v194, 16, v146
	v_and_b32_e32 v195, 0xffff0000, v146
	v_lshlrev_b32_e32 v202, 16, v148
	v_and_b32_e32 v203, 0xffff0000, v148
	v_lshlrev_b32_e32 v200, 16, v147
	v_and_b32_e32 v201, 0xffff0000, v147
	v_lshlrev_b32_e32 v204, 16, v149
	v_and_b32_e32 v205, 0xffff0000, v149
	v_pk_add_f32 v[124:125], v[124:125], v[194:195]
	v_pk_add_f32 v[120:121], v[120:121], v[202:203]
	v_pk_add_f32 v[126:127], v[126:127], v[200:201]
	v_lshlrev_b32_e32 v206, 16, v158
	v_and_b32_e32 v207, 0xffff0000, v158
	v_lshlrev_b32_e32 v158, 16, v159
	v_and_b32_e32 v159, 0xffff0000, v159
	v_lshlrev_b32_e32 v208, 16, v160
	v_lshlrev_b32_e32 v146, 16, v184
	v_and_b32_e32 v147, 0xffff0000, v184
	v_lshlrev_b32_e32 v150, 16, v185
	v_and_b32_e32 v151, 0xffff0000, v185
	v_lshl_add_u64 v[184:185], s[30:31], 0, v[188:189]
	v_pk_add_f32 v[188:189], v[122:123], v[204:205]
	v_cvt_pk_bf16_f32 v122, v124, v125
	v_cvt_pk_bf16_f32 v124, v120, v121
	v_lshlrev_b64 v[120:121], 1, v[186:187]
	v_and_b32_e32 v209, 0xffff0000, v160
	v_lshlrev_b32_e32 v160, 16, v161
	v_and_b32_e32 v161, 0xffff0000, v161
	v_cvt_pk_bf16_f32 v123, v126, v127
	v_lshl_add_u64 v[126:127], v[184:185], 0, v[120:121]
	v_cvt_pk_bf16_f32 v125, v188, v189
	global_store_dwordx4 v[126:127], v[122:125], off
	v_pk_add_f32 v[118:119], v[118:119], v[158:159]
	v_pk_add_f32 v[116:117], v[116:117], v[206:207]
	v_pk_add_f32 v[122:123], v[110:111], v[160:161]
	v_pk_add_f32 v[110:111], v[108:109], v[208:209]
	v_cvt_pk_bf16_f32 v108, v116, v117
	v_cvt_pk_bf16_f32 v109, v118, v119
	v_lshlrev_b32_e32 v210, 16, v162
	v_and_b32_e32 v211, 0xffff0000, v162
	v_lshlrev_b32_e32 v162, 16, v163
	v_and_b32_e32 v163, 0xffff0000, v163
	v_lshlrev_b32_e32 v212, 16, v164
	v_and_b32_e32 v213, 0xffff0000, v164
	v_lshlrev_b32_e32 v164, 16, v165
	v_and_b32_e32 v165, 0xffff0000, v165
	v_cvt_pk_bf16_f32 v110, v110, v111
	v_cvt_pk_bf16_f32 v111, v122, v123
	global_store_dwordx4 v[126:127], v[108:111], off offset:256
	v_lshlrev_b32_e32 v214, 16, v166
	v_and_b32_e32 v215, 0xffff0000, v166
	v_lshl_add_u64 v[108:109], s[30:31], 0, v[190:191]
	v_lshlrev_b32_e32 v166, 16, v167
	v_and_b32_e32 v167, 0xffff0000, v167
	v_lshlrev_b32_e32 v216, 16, v168
	v_and_b32_e32 v217, 0xffff0000, v168
	v_lshlrev_b32_e32 v168, 16, v169
	v_and_b32_e32 v169, 0xffff0000, v169
	v_pk_add_f32 v[110:111], v[114:115], v[162:163]
	v_pk_add_f32 v[112:113], v[112:113], v[210:211]
	v_pk_add_f32 v[114:115], v[106:107], v[164:165]
	v_pk_add_f32 v[106:107], v[104:105], v[212:213]
	v_cvt_pk_bf16_f32 v104, v112, v113
	v_cvt_pk_bf16_f32 v105, v110, v111
	v_lshl_add_u64 v[108:109], v[108:109], 0, v[120:121]
	v_cvt_pk_bf16_f32 v106, v106, v107
	v_cvt_pk_bf16_f32 v107, v114, v115
	global_store_dwordx4 v[108:109], v[104:107], off
	v_pk_add_f32 v[102:103], v[102:103], v[166:167]
	v_pk_add_f32 v[100:101], v[100:101], v[214:215]
	v_pk_add_f32 v[104:105], v[94:95], v[168:169]
	v_pk_add_f32 v[94:95], v[92:93], v[216:217]
	v_cvt_pk_bf16_f32 v92, v100, v101
	v_cvt_pk_bf16_f32 v93, v102, v103
	v_lshlrev_b32_e32 v218, 16, v170
	v_and_b32_e32 v219, 0xffff0000, v170
	v_lshlrev_b32_e32 v170, 16, v171
	v_and_b32_e32 v171, 0xffff0000, v171
	v_lshlrev_b32_e32 v220, 16, v172
	v_and_b32_e32 v221, 0xffff0000, v172
	v_lshlrev_b32_e32 v172, 16, v173
	v_and_b32_e32 v173, 0xffff0000, v173
	v_cvt_pk_bf16_f32 v94, v94, v95
	v_cvt_pk_bf16_f32 v95, v104, v105
	global_store_dwordx4 v[108:109], v[92:95], off offset:256
	v_lshlrev_b32_e32 v222, 16, v174
	v_and_b32_e32 v223, 0xffff0000, v174
	v_lshl_add_u64 v[92:93], s[30:31], 0, v[192:193]
; __device__ __forceinline__ unsigned cvt_pk(float lo, float hi) { unsigned r; asm("v_cvt_pk_bf16_f32 %0, %1, %2" : "=v"(r) : "v"(lo), "v"(hi)); return r; }
;     __device__ __forceinline__ void operator()(AccRef acc, const pg8::Unit& u, int wr, int wc, int, int) const {
;     ...
;                 for (int m = 0; m < 4; ++m) { const int row = u.pm * 256 + ai * 128 + wr * 64 + m * 16 + fr;
; #pragma unroll
;                     for (int bj = 0; bj < 2; ++bj) pw[m][bj] = *(const v4u*)(RB + (size_t)row * DM + u.pn * 256 + bj * 128 + wc * 32 + 8 * fq); }
; #pragma unroll
;                 for (int m = 0; m < 4; ++m)
; #pragma unroll
;                     for (int bj = 0; bj < 2; ++bj) { const v4u w = pw[m][bj]; r0[m][bj] = (f32x4){bf_lo(w.x), bf_hi(w.x), bf_lo(w.y), bf_hi(w.y)}; r1[m][bj] = (f32x4){bf_lo(w.z), bf_hi(w.z), bf_lo(w.w), bf_hi(w.w)}; }
;             }
;             asm volatile("" ::: "memory");
; #pragma unroll
;             for (int m = 0; m < 4; ++m) {
;                 const int row = u.pm * 256 + ai * 128 + wr * 64 + m * 16 + fr;
;                 float ss = 0.f;
; #pragma unroll
;                 for (int bj = 0; bj < 2; ++bj) {
;                     const int c0 = u.pn * 256 + bj * 128 + wc * 32 + 8 * fq;
;                     const f32x4 o0 = r0[m][bj] + acc[ai][bj][m][0], o1 = r1[m][bj] + acc[ai][bj][m][1];
;                     v4u w; w.x = cvt_pk(o0[0], o0[1]); w.y = cvt_pk(o0[2], o0[3]); w.z = cvt_pk(o1[0], o1[1]); w.w = cvt_pk(o1[2], o1[3]);
;                     *(v4u*)(HB + (size_t)row * DM + c0) = w;
	v_lshlrev_b32_e32 v174, 16, v175
	v_and_b32_e32 v175, 0xffff0000, v175
	v_lshlrev_b32_e32 v224, 16, v176
	v_and_b32_e32 v225, 0xffff0000, v176
	v_lshlrev_b32_e32 v176, 16, v177
	v_and_b32_e32 v177, 0xffff0000, v177
	v_pk_add_f32 v[94:95], v[98:99], v[170:171]
	v_pk_add_f32 v[96:97], v[96:97], v[218:219]
	v_pk_add_f32 v[98:99], v[90:91], v[172:173]
	v_pk_add_f32 v[90:91], v[88:89], v[220:221]
	v_cvt_pk_bf16_f32 v88, v96, v97
	v_cvt_pk_bf16_f32 v89, v94, v95
	v_lshl_add_u64 v[92:93], v[92:93], 0, v[120:121]
	v_cvt_pk_bf16_f32 v90, v90, v91
	v_cvt_pk_bf16_f32 v91, v98, v99
	global_store_dwordx4 v[92:93], v[88:91], off
	v_pk_add_f32 v[86:87], v[86:87], v[174:175]
	v_pk_add_f32 v[84:85], v[84:85], v[222:223]
	v_pk_add_f32 v[88:89], v[78:79], v[176:177]
	v_pk_add_f32 v[78:79], v[76:77], v[224:225]
	v_cvt_pk_bf16_f32 v76, v84, v85
	v_cvt_pk_bf16_f32 v77, v86, v87
	v_lshlrev_b32_e32 v226, 16, v178
	v_and_b32_e32 v227, 0xffff0000, v178
	v_lshlrev_b32_e32 v178, 16, v179
	v_and_b32_e32 v179, 0xffff0000, v179
	v_lshlrev_b32_e32 v228, 16, v180
	v_and_b32_e32 v229, 0xffff0000, v180
	v_lshlrev_b32_e32 v180, 16, v181
	v_and_b32_e32 v181, 0xffff0000, v181
	v_cvt_pk_bf16_f32 v78, v78, v79
	v_cvt_pk_bf16_f32 v79, v88, v89
	global_store_dwordx4 v[92:93], v[76:79], off offset:256
	v_lshlrev_b32_e32 v148, 16, v182
	v_and_b32_e32 v149, 0xffff0000, v182
	v_lshl_add_u64 v[76:77], s[30:31], 0, v[144:145]
	v_pk_add_f32 v[78:79], v[82:83], v[178:179]
	v_pk_add_f32 v[80:81], v[80:81], v[226:227]
	v_pk_add_f32 v[82:83], v[74:75], v[180:181]
	v_pk_add_f32 v[74:75], v[72:73], v[228:229]
	v_cvt_pk_bf16_f32 v72, v80, v81
	v_cvt_pk_bf16_f32 v73, v78, v79
	v_lshl_add_u64 v[76:77], v[76:77], 0, v[120:121]
	v_lshlrev_b32_e32 v182, 16, v183
	v_and_b32_e32 v183, 0xffff0000, v183
	v_cvt_pk_bf16_f32 v74, v74, v75
	v_cvt_pk_bf16_f32 v75, v82, v83
	global_store_dwordx4 v[76:77], v[72:75], off
	v_pk_add_f32 v[68:69], v[68:69], v[148:149]
	v_pk_add_f32 v[70:71], v[70:71], v[182:183]
	v_pk_add_f32 v[72:73], v[66:67], v[150:151]
	v_pk_add_f32 v[66:67], v[64:65], v[146:147]
	v_cvt_pk_bf16_f32 v64, v68, v69
	v_cvt_pk_bf16_f32 v65, v70, v71
	s_nop 0
	v_cvt_pk_bf16_f32 v66, v66, v67
	v_cvt_pk_bf16_f32 v67, v72, v73
	global_store_dwordx4 v[76:77], v[64:67], off offset:256
	s_nop 1
	v_add_u32_e32 v64, 0x80, v140
	v_ashrrev_i32_e32 v65, 31, v64
	v_lshlrev_b64 v[98:99], 11, v[64:65]
	v_lshl_add_u64 v[64:65], v[142:143], 0, v[98:99]
	v_mov_b64_e32 v[66:67], v[230:231]
	v_mov_b64_e32 v[68:69], v[232:233]
	v_mov_b64_e32 v[70:71], v[234:235]
	v_mov_b64_e32 v[72:73], v[236:237]
	v_add_u32_e32 v64, 0x90, v140
	v_ashrrev_i32_e32 v65, 31, v64
	v_lshlrev_b64 v[100:101], 11, v[64:65]
	v_lshl_add_u64 v[64:65], v[142:143], 0, v[100:101]
	v_mov_b64_e32 v[74:75], v[238:239]
	v_mov_b64_e32 v[76:77], v[240:241]
	v_mov_b64_e32 v[78:79], v[242:243]
	v_mov_b64_e32 v[80:81], v[244:245]
	v_add_u32_e32 v64, 0xa0, v140
	v_ashrrev_i32_e32 v65, 31, v64
	v_lshlrev_b64 v[102:103], 11, v[64:65]
	v_lshl_add_u64 v[64:65], v[142:143], 0, v[102:103]
	global_load_dwordx4 v[82:85], v[64:65], off
	global_load_dwordx4 v[86:89], v[64:65], off offset:256
	v_add_u32_e32 v64, 0xb0, v140
	v_ashrrev_i32_e32 v65, 31, v64
	v_lshlrev_b64 v[64:65], 11, v[64:65]
	v_lshl_add_u64 v[94:95], v[142:143], 0, v[64:65]
	global_load_dwordx4 v[90:93], v[94:95], off
	s_nop 0
	global_load_dwordx4 v[94:97], v[94:95], off offset:256
	v_lshl_add_u64 v[98:99], s[30:31], 0, v[98:99]
	v_lshlrev_b32_e32 v104, 16, v66
	v_and_b32_e32 v105, 0xffff0000, v66
	v_lshlrev_b32_e32 v106, 16, v67
	v_and_b32_e32 v107, 0xffff0000, v67
	v_lshlrev_b32_e32 v108, 16, v68
	v_and_b32_e32 v109, 0xffff0000, v68
	v_lshlrev_b32_e32 v110, 16, v69
	v_and_b32_e32 v111, 0xffff0000, v69
	v_pk_add_f32 v[60:61], v[60:61], v[104:105]
	v_lshlrev_b32_e32 v112, 16, v70
	v_and_b32_e32 v113, 0xffff0000, v70
	v_lshlrev_b32_e32 v70, 16, v71
	v_and_b32_e32 v71, 0xffff0000, v71
	v_lshlrev_b32_e32 v114, 16, v72
	v_and_b32_e32 v115, 0xffff0000, v72
	v_lshlrev_b32_e32 v72, 16, v73
	v_and_b32_e32 v73, 0xffff0000, v73
	v_pk_add_f32 v[62:63], v[62:63], v[106:107]
	v_pk_add_f32 v[104:105], v[58:59], v[110:111]
	v_pk_add_f32 v[58:59], v[56:57], v[108:109]
	v_cvt_pk_bf16_f32 v56, v60, v61
	v_cvt_pk_bf16_f32 v57, v62, v63
	v_lshl_add_u64 v[60:61], v[98:99], 0, v[120:121]
	v_cvt_pk_bf16_f32 v58, v58, v59
	v_cvt_pk_bf16_f32 v59, v104, v105
	global_store_dwordx4 v[60:61], v[56:59], off
	v_pk_add_f32 v[54:55], v[54:55], v[70:71]
	v_pk_add_f32 v[52:53], v[52:53], v[112:113]
	v_pk_add_f32 v[56:57], v[46:47], v[72:73]
	v_pk_add_f32 v[46:47], v[44:45], v[114:115]
	v_cvt_pk_bf16_f32 v44, v52, v53
	v_cvt_pk_bf16_f32 v45, v54, v55
	v_lshlrev_b32_e32 v116, 16, v74
	v_and_b32_e32 v117, 0xffff0000, v74
	v_lshlrev_b32_e32 v74, 16, v75
	v_and_b32_e32 v75, 0xffff0000, v75
	v_lshlrev_b32_e32 v118, 16, v76
	v_and_b32_e32 v119, 0xffff0000, v76
	v_lshlrev_b32_e32 v76, 16, v77
	v_and_b32_e32 v77, 0xffff0000, v77
	v_cvt_pk_bf16_f32 v46, v46, v47
	v_cvt_pk_bf16_f32 v47, v56, v57
	global_store_dwordx4 v[60:61], v[44:47], off offset:256
	v_lshlrev_b32_e32 v122, 16, v78
	v_and_b32_e32 v123, 0xffff0000, v78
	v_lshl_add_u64 v[44:45], s[30:31], 0, v[100:101]
	v_lshlrev_b32_e32 v78, 16, v79
	v_and_b32_e32 v79, 0xffff0000, v79
	v_lshlrev_b32_e32 v124, 16, v80
	v_and_b32_e32 v125, 0xffff0000, v80
	v_lshlrev_b32_e32 v80, 16, v81
	v_and_b32_e32 v81, 0xffff0000, v81
	v_pk_add_f32 v[46:47], v[50:51], v[74:75]
	v_pk_add_f32 v[48:49], v[48:49], v[116:117]
	v_pk_add_f32 v[50:51], v[42:43], v[76:77]
	v_pk_add_f32 v[42:43], v[40:41], v[118:119]
	v_cvt_pk_bf16_f32 v40, v48, v49
	v_cvt_pk_bf16_f32 v41, v46, v47
	v_lshl_add_u64 v[44:45], v[44:45], 0, v[120:121]
	v_cvt_pk_bf16_f32 v42, v42, v43
	v_cvt_pk_bf16_f32 v43, v50, v51
	global_store_dwordx4 v[44:45], v[40:43], off
	v_pk_add_f32 v[38:39], v[38:39], v[78:79]
	v_pk_add_f32 v[36:37], v[36:37], v[122:123]
	v_pk_add_f32 v[40:41], v[30:31], v[80:81]
	v_pk_add_f32 v[30:31], v[28:29], v[124:125]
	v_cvt_pk_bf16_f32 v28, v36, v37
	v_cvt_pk_bf16_f32 v29, v38, v39
	s_waitcnt vmcnt(6)
; __device__ __forceinline__ unsigned cvt_pk(float lo, float hi) { unsigned r; asm("v_cvt_pk_bf16_f32 %0, %1, %2" : "=v"(r) : "v"(lo), "v"(hi)); return r; }
; #define PG8_BAR __builtin_amdgcn_s_barrier()
; template <int KK, class Epi, class Sched, bool ALIGN_EPI = true>
; __device__ __forceinline__ void gemm_phase(LAS unsigned char* lds, const bf16* gA, const bf16* gBt, const Sched& S, const Epi& E, const int wid) {
;     ...
;         if constexpr (ALIGN_EPI) { if (wr == 0) PG8_BAR; }
;         E(acc, cur, wr, wc, fr, fq);
;         if (!has_next) break;
; #pragma unroll
;         for (int a = 0; a < 2; ++a)
; #pragma unroll
;             for (int b = 0; b < 2; ++b)
; #pragma unroll
;                 for (int m = 0; m < 4; ++m)
; #pragma unroll
;                     for (int n = 0; n < 2; ++n) acc[a][b][m][n] = (f32x4){0.f, 0.f, 0.f, 0.f};
;         cur = nxt; cA = nA; cB = nB; ++ui;
;         if constexpr (ALIGN_EPI) { if (wr == 1) PG8_BAR; }
;     __device__ __forceinline__ void operator()(AccRef acc, const pg8::Unit& u, int wr, int wc, int, int) const {
;     ...
;             for (int m = 0; m < 4; ++m) {
;                 const int row = u.pm * 256 + ai * 128 + wr * 64 + m * 16 + fr;
;                 float ss = 0.f;
; #pragma unroll
;                 for (int bj = 0; bj < 2; ++bj) {
;                     const int c0 = u.pn * 256 + bj * 128 + wc * 32 + 8 * fq;
;                     const f32x4 o0 = r0[m][bj] + acc[ai][bj][m][0], o1 = r1[m][bj] + acc[ai][bj][m][1];
;                     v4u w; w.x = cvt_pk(o0[0], o0[1]); w.y = cvt_pk(o0[2], o0[3]); w.z = cvt_pk(o1[0], o1[1]); w.w = cvt_pk(o1[2], o1[3]);
;                     *(v4u*)(HB + (size_t)row * DM + c0) = w;
;                     ss += (o0[0] * o0[0] + o0[1] * o0[1]) + (o0[2] * o0[2] + o0[3] * o0[3]) + (o1[0] * o1[0] + o1[1] * o1[1]) + (o1[2] * o1[2] + o1[3] * o1[3]);
;                 }
	v_lshlrev_b32_e32 v126, 16, v82
	v_and_b32_e32 v127, 0xffff0000, v82
	v_lshlrev_b32_e32 v82, 16, v83
	v_and_b32_e32 v83, 0xffff0000, v83
	v_lshlrev_b32_e32 v140, 16, v84
	v_and_b32_e32 v141, 0xffff0000, v84
	v_lshlrev_b32_e32 v84, 16, v85
	v_and_b32_e32 v85, 0xffff0000, v85
	v_cvt_pk_bf16_f32 v30, v30, v31
	v_cvt_pk_bf16_f32 v31, v40, v41
	global_store_dwordx4 v[44:45], v[28:31], off offset:256
	s_waitcnt vmcnt(6)
	v_lshlrev_b32_e32 v142, 16, v86
	v_and_b32_e32 v143, 0xffff0000, v86
	v_lshl_add_u64 v[28:29], s[30:31], 0, v[102:103]
	v_lshlrev_b32_e32 v86, 16, v87
	v_and_b32_e32 v87, 0xffff0000, v87
	v_lshlrev_b32_e32 v144, 16, v88
	v_and_b32_e32 v145, 0xffff0000, v88
	v_lshlrev_b32_e32 v88, 16, v89
	v_and_b32_e32 v89, 0xffff0000, v89
	v_pk_add_f32 v[30:31], v[34:35], v[82:83]
	v_pk_add_f32 v[32:33], v[32:33], v[126:127]
	v_pk_add_f32 v[34:35], v[26:27], v[84:85]
	v_pk_add_f32 v[26:27], v[24:25], v[140:141]
	v_cvt_pk_bf16_f32 v24, v32, v33
	v_cvt_pk_bf16_f32 v25, v30, v31
	v_lshl_add_u64 v[28:29], v[28:29], 0, v[120:121]
	v_cvt_pk_bf16_f32 v26, v26, v27
	v_cvt_pk_bf16_f32 v27, v34, v35
	global_store_dwordx4 v[28:29], v[24:27], off
	v_pk_add_f32 v[22:23], v[22:23], v[86:87]
	v_pk_add_f32 v[20:21], v[20:21], v[142:143]
	v_pk_add_f32 v[24:25], v[14:15], v[88:89]
	v_pk_add_f32 v[14:15], v[12:13], v[144:145]
	v_cvt_pk_bf16_f32 v12, v20, v21
	v_cvt_pk_bf16_f32 v13, v22, v23
	s_waitcnt vmcnt(6)
	v_lshlrev_b32_e32 v146, 16, v90
	v_and_b32_e32 v147, 0xffff0000, v90
	v_lshlrev_b32_e32 v90, 16, v91
	v_and_b32_e32 v91, 0xffff0000, v91
	v_lshlrev_b32_e32 v148, 16, v92
	v_and_b32_e32 v149, 0xffff0000, v92
	v_lshlrev_b32_e32 v92, 16, v93
	v_and_b32_e32 v93, 0xffff0000, v93
	v_cvt_pk_bf16_f32 v14, v14, v15
	v_cvt_pk_bf16_f32 v15, v24, v25
	global_store_dwordx4 v[28:29], v[12:15], off offset:256
	s_waitcnt vmcnt(6)
	v_lshlrev_b32_e32 v66, 16, v96
	v_and_b32_e32 v67, 0xffff0000, v96
	v_lshl_add_u64 v[12:13], s[30:31], 0, v[64:65]
	v_lshlrev_b32_e32 v96, 16, v97
	v_and_b32_e32 v97, 0xffff0000, v97
	v_pk_add_f32 v[14:15], v[18:19], v[90:91]
	v_pk_add_f32 v[16:17], v[16:17], v[146:147]
	v_pk_add_f32 v[18:19], v[10:11], v[92:93]
	v_pk_add_f32 v[10:11], v[8:9], v[148:149]
	v_cvt_pk_bf16_f32 v8, v16, v17
	v_cvt_pk_bf16_f32 v9, v14, v15
	v_lshl_add_u64 v[12:13], v[12:13], 0, v[120:121]
	v_lshlrev_b32_e32 v68, 16, v94
	v_and_b32_e32 v69, 0xffff0000, v94
	v_lshlrev_b32_e32 v94, 16, v95
	v_and_b32_e32 v95, 0xffff0000, v95
	v_cvt_pk_bf16_f32 v10, v10, v11
	v_cvt_pk_bf16_f32 v11, v18, v19
	global_store_dwordx4 v[12:13], v[8:11], off
	s_mov_b64 s[30:31], -1
	v_pk_add_f32 v[6:7], v[6:7], v[94:95]
	v_pk_add_f32 v[8:9], v[2:3], v[96:97]
	v_pk_add_f32 v[2:3], v[0:1], v[66:67]
	v_pk_add_f32 v[4:5], v[4:5], v[68:69]
	v_cvt_pk_bf16_f32 v1, v6, v7
	v_cvt_pk_bf16_f32 v2, v2, v3
	v_cvt_pk_bf16_f32 v3, v8, v9
	s_nop 0
	v_cvt_pk_bf16_f32 v0, v4, v5
	global_store_dwordx4 v[12:13], v[0:3], off offset:256
	s_cbranch_vccnz .LBB0_660
	s_andn2_b64 vcc, exec, s[12:13]
	s_cbranch_vccnz .LBB0_659
	s_barrier
	s_branch .LBB0_659

;     __device__ __forceinline__ void operator()(AccRef acc, const pg8::Unit& u, int wr, int wc, int, int) const {
;     ...
;         for (int ai = 0; ai < 2; ++ai) {
;             f32x4 r0[4][2], r1[4][2];
;             if (xp) {
; #pragma unroll
;                 for (int m = 0; m < 4; ++m) { const int row = u.pm * 256 + ai * 128 + wr * 64 + m * 16 + fr;
;                     const float* rsrc = (row < MP) ? xp + (size_t)row * DM : xs + (size_t)(row - MP) * DM;
; #pragma unroll
;                     for (int bj = 0; bj < 2; ++bj) { const int c0 = u.pn * 256 + bj * 128 + wc * 32 + 8 * fq; r0[m][bj] = *(const f32x4*)(rsrc + c0); r1[m][bj] = *(const f32x4*)(rsrc + c0 + 4); } }
;             } else {
;                 v4u pw[4][2];
; #pragma unroll
;                 for (int m = 0; m < 4; ++m) { const int row = u.pm * 256 + ai * 128 + wr * 64 + m * 16 + fr;
; #pragma unroll
;                     for (int bj = 0; bj < 2; ++bj) pw[m][bj] = *(const v4u*)(RB + (size_t)row * DM + u.pn * 256 + bj * 128 + wc * 32 + 8 * fq); }
; #pragma unroll
;                 for (int m = 0; m < 4; ++m)
; #pragma unroll
;                     for (int bj = 0; bj < 2; ++bj) { const v4u w = pw[m][bj]; r0[m][bj] = (f32x4){bf_lo(w.x), bf_hi(w.x), bf_lo(w.y), bf_hi(w.y)}; r1[m][bj] = (f32x4){bf_lo(w.z), bf_hi(w.z), bf_lo(w.w), bf_hi(w.w)}; }
;             }
;             asm volatile("" ::: "memory");
; #pragma unroll
;             for (int m = 0; m < 4; ++m) {
;                 const int row = u.pm * 256 + ai * 128 + wr * 64 + m * 16 + fr;
;                 float ss = 0.f;
; #pragma unroll
;                 for (int bj = 0; bj < 2; ++bj) {
;                     const int c0 = u.pn * 256 + bj * 128 + wc * 32 + 8 * fq;
;                     const f32x4 o0 = r0[m][bj] + acc[ai][bj][m][0], o1 = r1[m][bj] + acc[ai][bj][m][1];
;                     v4u w; w.x = cvt_pk(o0[0], o0[1]); w.y = cvt_pk(o0[2], o0[3]); w.z = cvt_pk(o1[0], o1[1]); w.w = cvt_pk(o1[2], o1[3]);
;                     *(v4u*)(HB + (size_t)row * DM + c0) = w;
;                     ss += (o0[0] * o0[0] + o0[1] * o0[1]) + (o0[2] * o0[2] + o0[3] * o0[3]) + (o1[0] * o1[0] + o1[1] * o1[1]) + (o1[2] * o1[2] + o1[3] * o1[3]);
;                 }
;                 if (ssq_off >= 0) { ss += __shfl_xor(ss, 16); ss += __shfl_xor(ss, 32); if (fq == 0) __hip_atomic_fetch_add(ssq + row, ss, __ATOMIC_RELAXED, __HIP_MEMORY_SCOPE_AGENT); }
.LBB0_1189:
	s_mov_b64 s[42:43], s[22:23]
	s_mov_b64 s[46:47], s[20:21]
	s_add_u32 s44, s46, 0x7800000
	s_addc_u32 s45, s47, 0
	s_add_u32 s42, s46, 0x64000
	s_addc_u32 s43, s47, 0
	s_lshl_b32 s15, s38, 8
	s_lshl_b32 s36, s36, 8
	v_mov_b32_e32 v187, v196
	s_add_i32 s15, s15, s35
	s_ashr_i32 s37, s36, 31
	s_nop 0
	v_and_or_b32 v166, v187, 15, s15
	s_or_b32 s15, s36, s28
	s_lshl_b64 s[36:37], s[36:37], 1
	s_add_u32 s17, s46, s36
	v_ashrrev_i32_e32 v128, 1, v187
	s_addc_u32 s37, s47, s37
	v_and_b32_e32 v164, -8, v128
	s_add_u32 s36, s17, s55
	s_addc_u32 s37, s37, 0
	v_ashrrev_i32_e32 v165, 31, v164
	v_lshl_add_u64 v[128:129], v[164:165], 1, s[36:37]
	v_ashrrev_i32_e32 v167, 31, v166
	v_lshl_add_u64 v[168:169], v[128:129], 0, s[12:13]
	v_lshlrev_b64 v[200:201], 11, v[166:167]
	v_lshl_add_u64 v[128:129], v[168:169], 0, v[200:201]
	s_mov_b64 s[56:57], 0x40000
	v_lshl_add_u64 v[244:245], v[128:129], 0, s[56:57]
	global_load_dwordx4 v[188:191], v[128:129], off
	global_load_dwordx4 v[192:195], v[128:129], off offset:256
	global_load_dwordx4 v[212:215], v[244:245], off
	global_load_dwordx4 v[216:219], v[244:245], off offset:256
	v_or_b32_e32 v176, 16, v166
	v_or_b32_e32 v174, 32, v166
	v_or_b32_e32 v170, 48, v166
	v_ashrrev_i32_e32 v177, 31, v176
	v_ashrrev_i32_e32 v175, 31, v174
	v_ashrrev_i32_e32 v171, 31, v170
	v_lshlrev_b64 v[180:181], 11, v[176:177]
	v_lshlrev_b64 v[178:179], 11, v[174:175]
	v_lshlrev_b64 v[172:173], 11, v[170:171]
	v_lshl_add_u64 v[128:129], v[168:169], 0, v[180:181]
	v_lshl_add_u64 v[130:131], v[168:169], 0, v[178:179]
	v_lshl_add_u64 v[202:203], v[168:169], 0, v[172:173]
	v_lshl_add_u64 v[244:245], v[128:129], 0, s[56:57]
	global_load_dwordx4 v[148:151], v[128:129], off
	global_load_dwordx4 v[144:147], v[128:129], off offset:256
	global_load_dwordx4 v[220:223], v[244:245], off
	global_load_dwordx4 v[224:227], v[244:245], off offset:256
	v_lshl_add_u64 v[244:245], v[130:131], 0, s[56:57]
	global_load_dwordx4 v[140:143], v[130:131], off
	global_load_dwordx4 v[136:139], v[130:131], off offset:256
	global_load_dwordx4 v[228:231], v[244:245], off
	global_load_dwordx4 v[232:235], v[244:245], off offset:256
	v_lshl_add_u64 v[244:245], v[202:203], 0, s[56:57]
	global_load_dwordx4 v[132:135], v[202:203], off
	s_nop 0
	global_load_dwordx4 v[128:131], v[202:203], off offset:256
	global_load_dwordx4 v[236:239], v[244:245], off
	global_load_dwordx4 v[240:243], v[244:245], off offset:256
	v_cmp_gt_u32_e32 vcc, 16, v187
	v_add_u32_e32 v164, s15, v164
	v_ashrrev_i32_e32 v165, 31, v164
	v_lshl_add_u64 v[200:201], s[44:45], 0, v[200:201]
	s_waitcnt vmcnt(0)
	v_lshlrev_b32_e32 v202, 16, v188
	v_and_b32_e32 v203, 0xffff0000, v188
	v_lshlrev_b32_e32 v188, 16, v189
	v_and_b32_e32 v189, 0xffff0000, v189
	v_lshlrev_b32_e32 v206, 16, v192
	v_and_b32_e32 v207, 0xffff0000, v192
	v_lshlrev_b32_e32 v192, 16, v193
	v_and_b32_e32 v193, 0xffff0000, v193
	v_lshlrev_b32_e32 v204, 16, v190
	v_and_b32_e32 v205, 0xffff0000, v190
	v_lshlrev_b32_e32 v190, 16, v191
	v_and_b32_e32 v191, 0xffff0000, v191
	v_lshlrev_b32_e32 v208, 16, v194
	v_and_b32_e32 v209, 0xffff0000, v194
	v_pk_add_f32 v[126:127], v[126:127], v[188:189]
	v_pk_add_f32 v[124:125], v[124:125], v[202:203]
	v_pk_add_f32 v[118:119], v[118:119], v[192:193]
	v_pk_add_f32 v[116:117], v[116:117], v[206:207]
	v_lshlrev_b32_e32 v194, 16, v195
	v_and_b32_e32 v195, 0xffff0000, v195
	v_pk_add_f32 v[122:123], v[122:123], v[190:191]
	v_pk_add_f32 v[120:121], v[120:121], v[204:205]
	v_pk_add_f32 v[190:191], v[112:113], v[208:209]
	v_cvt_pk_bf16_f32 v112, v124, v125
	v_cvt_pk_bf16_f32 v113, v126, v127
	v_mul_f32_e32 v125, v125, v125
	v_mul_f32_e32 v127, v127, v127
	v_mul_f32_e32 v192, v117, v117
	v_mul_f32_e32 v193, v119, v119
	v_pk_add_f32 v[188:189], v[114:115], v[194:195]
	v_cvt_pk_bf16_f32 v114, v120, v121
	v_mul_f32_e32 v121, v121, v121
	v_mul_f32_e32 v194, v191, v191
	v_fmac_f32_e32 v125, v124, v124
	v_fmac_f32_e32 v127, v126, v126
	v_fmac_f32_e32 v192, v116, v116
	v_fmac_f32_e32 v193, v118, v118
	v_mul_f32_e32 v115, v123, v123
	v_mul_f32_e32 v187, v189, v189
	v_fmac_f32_e32 v121, v120, v120
	v_fmac_f32_e32 v194, v190, v190
	v_add_f32_e32 v120, v125, v127
	v_add_f32_e32 v124, v192, v193
	v_fmac_f32_e32 v115, v122, v122
	v_fmac_f32_e32 v187, v188, v188
	v_add_f32_e32 v120, v121, v120
	v_add_f32_e32 v121, v194, v124
	v_add_f32_e32 v115, v115, v120
	v_add_f32_e32 v120, v187, v121
	v_add_f32_e32 v124, v115, v120
	ds_bpermute_b32 v125, v197, v124
	v_lshl_add_u64 v[120:121], v[164:165], 1, v[200:201]
	v_cvt_pk_bf16_f32 v115, v122, v123
	global_store_dwordx4 v[120:121], v[112:115], off
	s_waitcnt lgkmcnt(0)
	s_nop 0
	v_add_f32_e32 v112, v124, v125
	ds_bpermute_b32 v113, v198, v112
	v_cvt_pk_bf16_f32 v114, v116, v117
	v_cvt_pk_bf16_f32 v115, v118, v119
	v_cvt_pk_bf16_f32 v116, v190, v191
	v_cvt_pk_bf16_f32 v117, v188, v189
	global_store_dwordx4 v[120:121], v[114:117], off offset:256
	s_and_saveexec_b64 s[36:37], vcc
	s_cbranch_execz .LBB0_1191
	s_waitcnt lgkmcnt(0)
	v_add_f32_e32 v114, v112, v113
	v_lshl_add_u64 v[112:113], v[166:167], 2, s[42:43]
	global_atomic_add_f32 v[112:113], v114, off

;     __device__ __forceinline__ void operator()(AccRef acc, const pg8::Unit& u, int wr, int wc, int, int) const {
;     ...
; #pragma unroll
;                 for (int m = 0; m < 4; ++m) { const int row = u.pm * 256 + ai * 128 + wr * 64 + m * 16 + fr;
;                     const float* rsrc = (row < MP) ? xp + (size_t)row * DM : xs + (size_t)(row - MP) * DM;
; #pragma unroll
;                     for (int bj = 0; bj < 2; ++bj) { const int c0 = u.pn * 256 + bj * 128 + wc * 32 + 8 * fq; r0[m][bj] = *(const f32x4*)(rsrc + c0); r1[m][bj] = *(const f32x4*)(rsrc + c0 + 4); } }
;             } else {
;                 v4u pw[4][2];
; #pragma unroll
;                 for (int m = 0; m < 4; ++m) { const int row = u.pm * 256 + ai * 128 + wr * 64 + m * 16 + fr;
; #pragma unroll
;                     for (int bj = 0; bj < 2; ++bj) pw[m][bj] = *(const v4u*)(RB + (size_t)row * DM + u.pn * 256 + bj * 128 + wc * 32 + 8 * fq); }
; #pragma unroll
;                 for (int m = 0; m < 4; ++m)
; #pragma unroll
;                     for (int bj = 0; bj < 2; ++bj) { const v4u w = pw[m][bj]; r0[m][bj] = (f32x4){bf_lo(w.x), bf_hi(w.x), bf_lo(w.y), bf_hi(w.y)}; r1[m][bj] = (f32x4){bf_lo(w.z), bf_hi(w.z), bf_lo(w.w), bf_hi(w.w)}; }
;             }
;             asm volatile("" ::: "memory");
; #pragma unroll
;             for (int m = 0; m < 4; ++m) {
;                 const int row = u.pm * 256 + ai * 128 + wr * 64 + m * 16 + fr;
;                 float ss = 0.f;
; #pragma unroll
;                 for (int bj = 0; bj < 2; ++bj) {
;                     const int c0 = u.pn * 256 + bj * 128 + wc * 32 + 8 * fq;
;                     const f32x4 o0 = r0[m][bj] + acc[ai][bj][m][0], o1 = r1[m][bj] + acc[ai][bj][m][1];
;                     v4u w; w.x = cvt_pk(o0[0], o0[1]); w.y = cvt_pk(o0[2], o0[3]); w.z = cvt_pk(o1[0], o1[1]); w.w = cvt_pk(o1[2], o1[3]);
;                     *(v4u*)(HB + (size_t)row * DM + c0) = w;
;                     ss += (o0[0] * o0[0] + o0[1] * o0[1]) + (o0[2] * o0[2] + o0[3] * o0[3]) + (o1[0] * o1[0] + o1[1] * o1[1]) + (o1[2] * o1[2] + o1[3] * o1[3]);
;                 }
;                 if (ssq_off >= 0) { ss += __shfl_xor(ss, 16); ss += __shfl_xor(ss, 32); if (fq == 0) __hip_atomic_fetch_add(ssq + row, ss, __ATOMIC_RELAXED, __HIP_MEMORY_SCOPE_AGENT); }
.LBB0_1197:
	s_or_b64 exec, exec, s[36:37]
	v_add_u32_e32 v98, 0x80, v166
	v_ashrrev_i32_e32 v99, 31, v98
	v_lshlrev_b64 v[110:111], 11, v[98:99]
	s_waitcnt lgkmcnt(0)
	v_lshl_add_u64 v[64:65], v[168:169], 0, v[110:111]
	v_mov_b64_e32 v[102:103], v[212:213]
	v_mov_b64_e32 v[104:105], v[214:215]
	v_mov_b64_e32 v[106:107], v[216:217]
	v_mov_b64_e32 v[108:109], v[218:219]
	v_add_u32_e32 v94, 0x90, v166
	v_add_u32_e32 v92, 0xa0, v166
	v_add_u32_e32 v88, 0xb0, v166
	v_ashrrev_i32_e32 v95, 31, v94
	v_ashrrev_i32_e32 v93, 31, v92
	v_ashrrev_i32_e32 v89, 31, v88
	v_lshlrev_b64 v[100:101], 11, v[94:95]
	v_lshlrev_b64 v[96:97], 11, v[92:93]
	v_lshlrev_b64 v[90:91], 11, v[88:89]
	v_lshl_add_u64 v[64:65], v[168:169], 0, v[100:101]
	v_lshl_add_u64 v[66:67], v[168:169], 0, v[96:97]
	v_lshl_add_u64 v[112:113], v[168:169], 0, v[90:91]
	v_mov_b64_e32 v[84:85], v[220:221]
	v_mov_b64_e32 v[86:87], v[222:223]
	v_mov_b64_e32 v[80:81], v[224:225]
	v_mov_b64_e32 v[82:83], v[226:227]
	v_mov_b64_e32 v[76:77], v[228:229]
	v_mov_b64_e32 v[78:79], v[230:231]
	v_mov_b64_e32 v[72:73], v[232:233]
	v_mov_b64_e32 v[74:75], v[234:235]
	v_mov_b64_e32 v[68:69], v[236:237]
	v_mov_b64_e32 v[70:71], v[238:239]
	s_nop 0
	v_mov_b64_e32 v[64:65], v[240:241]
	v_mov_b64_e32 v[66:67], v[242:243]
	v_lshl_add_u64 v[110:111], s[44:45], 0, v[110:111]
	v_lshlrev_b32_e32 v112, 16, v102
	v_and_b32_e32 v113, 0xffff0000, v102
	v_lshlrev_b32_e32 v102, 16, v103
	v_and_b32_e32 v103, 0xffff0000, v103
	v_lshlrev_b32_e32 v116, 16, v106
	v_and_b32_e32 v117, 0xffff0000, v106
	v_lshlrev_b32_e32 v106, 16, v107
	v_and_b32_e32 v107, 0xffff0000, v107
	v_lshlrev_b32_e32 v114, 16, v104
	v_and_b32_e32 v115, 0xffff0000, v104
	v_lshlrev_b32_e32 v104, 16, v105
	v_and_b32_e32 v105, 0xffff0000, v105
	v_lshlrev_b32_e32 v118, 16, v108
	v_and_b32_e32 v119, 0xffff0000, v108
	v_lshlrev_b32_e32 v108, 16, v109
	v_and_b32_e32 v109, 0xffff0000, v109
	v_pk_add_f32 v[62:63], v[62:63], v[102:103]
	v_pk_add_f32 v[60:61], v[60:61], v[112:113]
	v_pk_add_f32 v[54:55], v[54:55], v[106:107]
	v_pk_add_f32 v[52:53], v[52:53], v[116:117]
	v_pk_add_f32 v[58:59], v[58:59], v[104:105]
	v_pk_add_f32 v[56:57], v[56:57], v[114:115]
	v_pk_add_f32 v[102:103], v[50:51], v[108:109]
	v_pk_add_f32 v[104:105], v[48:49], v[118:119]
	v_cvt_pk_bf16_f32 v48, v60, v61
	v_cvt_pk_bf16_f32 v49, v62, v63
	v_mul_f32_e32 v61, v61, v61
	v_mul_f32_e32 v63, v63, v63
	v_mul_f32_e32 v107, v53, v53
	v_mul_f32_e32 v108, v55, v55
	v_cvt_pk_bf16_f32 v50, v56, v57
	v_mul_f32_e32 v57, v57, v57
	v_mul_f32_e32 v109, v105, v105
	v_fmac_f32_e32 v61, v60, v60
	v_fmac_f32_e32 v63, v62, v62
	v_fmac_f32_e32 v107, v52, v52
	v_fmac_f32_e32 v108, v54, v54
	v_mul_f32_e32 v51, v59, v59
	v_mul_f32_e32 v106, v103, v103
	v_fmac_f32_e32 v57, v56, v56
	v_fmac_f32_e32 v109, v104, v104
	v_add_f32_e32 v56, v61, v63
	v_add_f32_e32 v60, v107, v108
	v_fmac_f32_e32 v51, v58, v58
	v_fmac_f32_e32 v106, v102, v102
	v_add_f32_e32 v56, v57, v56
	v_add_f32_e32 v57, v109, v60
	v_add_f32_e32 v51, v51, v56
	v_add_f32_e32 v56, v106, v57
	v_add_f32_e32 v60, v51, v56
	ds_bpermute_b32 v61, v197, v60
	v_lshl_add_u64 v[56:57], v[164:165], 1, v[110:111]
	v_cvt_pk_bf16_f32 v51, v58, v59
	global_store_dwordx4 v[56:57], v[48:51], off
	s_waitcnt lgkmcnt(0)
	s_nop 0
	v_add_f32_e32 v48, v60, v61
	ds_bpermute_b32 v49, v198, v48
	v_cvt_pk_bf16_f32 v50, v52, v53
	v_cvt_pk_bf16_f32 v51, v54, v55
	v_cvt_pk_bf16_f32 v52, v104, v105
	v_cvt_pk_bf16_f32 v53, v102, v103
	global_store_dwordx4 v[56:57], v[50:53], off offset:256
	s_and_saveexec_b64 s[36:37], vcc
	s_cbranch_execz .LBB0_1199
	s_waitcnt lgkmcnt(0)
	v_add_f32_e32 v50, v48, v49
	v_lshl_add_u64 v[48:49], v[98:99], 2, s[42:43]
	global_atomic_add_f32 v[48:49], v50, off
.LBB0_1199:
	s_or_b64 exec, exec, s[36:37]
	v_lshlrev_b32_e32 v48, 16, v84
	s_waitcnt lgkmcnt(0)
	v_and_b32_e32 v49, 0xffff0000, v84
	v_lshlrev_b32_e32 v50, 16, v85
	v_and_b32_e32 v51, 0xffff0000, v85
	v_lshlrev_b32_e32 v52, 16, v86
	v_and_b32_e32 v53, 0xffff0000, v86
	v_lshlrev_b32_e32 v54, 16, v87
	v_and_b32_e32 v55, 0xffff0000, v87
	v_lshlrev_b32_e32 v60, 16, v82
	v_and_b32_e32 v61, 0xffff0000, v82
	v_lshlrev_b32_e32 v62, 16, v83
	v_and_b32_e32 v63, 0xffff0000, v83
	v_pk_add_f32 v[46:47], v[46:47], v[50:51]
	v_pk_add_f32 v[44:45], v[44:45], v[48:49]
	v_pk_add_f32 v[48:49], v[42:43], v[54:55]
	v_pk_add_f32 v[50:51], v[40:41], v[52:53]
	v_pk_add_f32 v[52:53], v[34:35], v[62:63]
	v_pk_add_f32 v[54:55], v[32:33], v[60:61]
	v_mul_f32_e32 v33, v45, v45
	v_mul_f32_e32 v34, v47, v47
	v_fmac_f32_e32 v33, v44, v44
	v_fmac_f32_e32 v34, v46, v46
	v_lshlrev_b32_e32 v56, 16, v80
	v_and_b32_e32 v57, 0xffff0000, v80
	v_lshlrev_b32_e32 v58, 16, v81
	v_and_b32_e32 v59, 0xffff0000, v81
	v_add_f32_e32 v33, v33, v34
	v_mul_f32_e32 v34, v51, v51
	v_pk_add_f32 v[38:39], v[38:39], v[58:59]
	v_pk_add_f32 v[36:37], v[36:37], v[56:57]
	v_fmac_f32_e32 v34, v50, v50
	v_add_f32_e32 v33, v34, v33
	v_mul_f32_e32 v34, v37, v37
	v_mul_f32_e32 v35, v39, v39
	v_mul_f32_e32 v32, v49, v49
	v_fmac_f32_e32 v34, v36, v36
	v_fmac_f32_e32 v35, v38, v38
	v_fmac_f32_e32 v32, v48, v48
	v_add_f32_e32 v34, v34, v35
	v_mul_f32_e32 v35, v55, v55
	v_add_f32_e32 v32, v32, v33
	v_mul_f32_e32 v33, v53, v53
	v_fmac_f32_e32 v35, v54, v54
	v_fmac_f32_e32 v33, v52, v52
	v_add_f32_e32 v34, v35, v34
	v_add_f32_e32 v33, v33, v34
	v_add_f32_e32 v32, v32, v33
	ds_bpermute_b32 v33, v197, v32
	v_lshl_add_u64 v[80:81], s[44:45], 0, v[100:101]
	v_cvt_pk_bf16_f32 v40, v44, v45
	v_lshl_add_u64 v[44:45], v[164:165], 1, v[80:81]
	v_cvt_pk_bf16_f32 v41, v46, v47
	s_waitcnt lgkmcnt(0)
	v_add_f32_e32 v32, v32, v33
	ds_bpermute_b32 v33, v198, v32
	v_cvt_pk_bf16_f32 v42, v50, v51
	v_cvt_pk_bf16_f32 v43, v48, v49
	global_store_dwordx4 v[44:45], v[40:43], off
	v_cvt_pk_bf16_f32 v34, v36, v37
	v_cvt_pk_bf16_f32 v35, v38, v39
	v_cvt_pk_bf16_f32 v36, v54, v55
	v_cvt_pk_bf16_f32 v37, v52, v53
	global_store_dwordx4 v[44:45], v[34:37], off offset:256
	s_and_saveexec_b64 s[36:37], vcc
	s_cbranch_execz .LBB0_1201
	s_waitcnt lgkmcnt(0)
	v_add_f32_e32 v34, v32, v33
	v_lshl_add_u64 v[32:33], v[94:95], 2, s[42:43]
	global_atomic_add_f32 v[32:33], v34, off
; __device__ __forceinline__ unsigned cvt_pk(float lo, float hi) { unsigned r; asm("v_cvt_pk_bf16_f32 %0, %1, %2" : "=v"(r) : "v"(lo), "v"(hi)); return r; }
;     __device__ __forceinline__ void operator()(AccRef acc, const pg8::Unit& u, int wr, int wc, int, int) const {
;     ...
;             for (int m = 0; m < 4; ++m) {
;                 const int row = u.pm * 256 + ai * 128 + wr * 64 + m * 16 + fr;
;                 float ss = 0.f;
; #pragma unroll
;                 for (int bj = 0; bj < 2; ++bj) {
;                     const int c0 = u.pn * 256 + bj * 128 + wc * 32 + 8 * fq;
;                     const f32x4 o0 = r0[m][bj] + acc[ai][bj][m][0], o1 = r1[m][bj] + acc[ai][bj][m][1];
;                     v4u w; w.x = cvt_pk(o0[0], o0[1]); w.y = cvt_pk(o0[2], o0[3]); w.z = cvt_pk(o1[0], o1[1]); w.w = cvt_pk(o1[2], o1[3]);
;                     *(v4u*)(HB + (size_t)row * DM + c0) = w;
;                     ss += (o0[0] * o0[0] + o0[1] * o0[1]) + (o0[2] * o0[2] + o0[3] * o0[3]) + (o1[0] * o1[0] + o1[1] * o1[1]) + (o1[2] * o1[2] + o1[3] * o1[3]);
;                 }
;                 if (ssq_off >= 0) { ss += __shfl_xor(ss, 16); ss += __shfl_xor(ss, 32); if (fq == 0) __hip_atomic_fetch_add(ssq + row, ss, __ATOMIC_RELAXED, __HIP_MEMORY_SCOPE_AGENT); }
.LBB0_1201:
	s_or_b64 exec, exec, s[36:37]
	v_lshlrev_b32_e32 v32, 16, v76
	s_waitcnt lgkmcnt(0)
	v_and_b32_e32 v33, 0xffff0000, v76
	v_lshlrev_b32_e32 v34, 16, v77
	v_and_b32_e32 v35, 0xffff0000, v77
	v_lshlrev_b32_e32 v36, 16, v78
	v_and_b32_e32 v37, 0xffff0000, v78
	v_lshlrev_b32_e32 v38, 16, v79
	v_and_b32_e32 v39, 0xffff0000, v79
	v_lshlrev_b32_e32 v44, 16, v74
	v_and_b32_e32 v45, 0xffff0000, v74
	v_lshlrev_b32_e32 v46, 16, v75
	v_and_b32_e32 v47, 0xffff0000, v75
	v_pk_add_f32 v[30:31], v[30:31], v[34:35]
	v_pk_add_f32 v[28:29], v[28:29], v[32:33]
	v_pk_add_f32 v[32:33], v[26:27], v[38:39]
	v_pk_add_f32 v[34:35], v[24:25], v[36:37]
	v_pk_add_f32 v[36:37], v[18:19], v[46:47]
	v_pk_add_f32 v[38:39], v[16:17], v[44:45]
	v_mul_f32_e32 v17, v29, v29
	v_mul_f32_e32 v18, v31, v31
	v_fmac_f32_e32 v17, v28, v28
	v_fmac_f32_e32 v18, v30, v30
	v_lshlrev_b32_e32 v40, 16, v72
	v_and_b32_e32 v41, 0xffff0000, v72
	v_lshlrev_b32_e32 v42, 16, v73
	v_and_b32_e32 v43, 0xffff0000, v73
	v_add_f32_e32 v17, v17, v18
	v_mul_f32_e32 v18, v35, v35
	v_pk_add_f32 v[22:23], v[22:23], v[42:43]
	v_pk_add_f32 v[20:21], v[20:21], v[40:41]
	v_fmac_f32_e32 v18, v34, v34
	v_add_f32_e32 v17, v18, v17
	v_mul_f32_e32 v18, v21, v21
	v_mul_f32_e32 v19, v23, v23
	v_mul_f32_e32 v16, v33, v33
	v_fmac_f32_e32 v18, v20, v20
	v_fmac_f32_e32 v19, v22, v22
	v_fmac_f32_e32 v16, v32, v32
	v_add_f32_e32 v18, v18, v19
	v_mul_f32_e32 v19, v39, v39
	v_add_f32_e32 v16, v16, v17
	v_mul_f32_e32 v17, v37, v37
	v_fmac_f32_e32 v19, v38, v38
	v_fmac_f32_e32 v17, v36, v36
	v_add_f32_e32 v18, v19, v18
	v_add_f32_e32 v17, v17, v18
	v_add_f32_e32 v16, v16, v17
	ds_bpermute_b32 v17, v197, v16
	v_lshl_add_u64 v[48:49], s[44:45], 0, v[96:97]
	v_cvt_pk_bf16_f32 v24, v28, v29
	v_lshl_add_u64 v[28:29], v[164:165], 1, v[48:49]
	v_cvt_pk_bf16_f32 v25, v30, v31
	s_waitcnt lgkmcnt(0)
	v_add_f32_e32 v16, v16, v17
	ds_bpermute_b32 v17, v198, v16
	v_cvt_pk_bf16_f32 v26, v34, v35
	v_cvt_pk_bf16_f32 v27, v32, v33
	global_store_dwordx4 v[28:29], v[24:27], off
	v_cvt_pk_bf16_f32 v18, v20, v21
	v_cvt_pk_bf16_f32 v19, v22, v23
	v_cvt_pk_bf16_f32 v20, v38, v39
	v_cvt_pk_bf16_f32 v21, v36, v37
	global_store_dwordx4 v[28:29], v[18:21], off offset:256
	s_and_saveexec_b64 s[36:37], vcc
	s_cbranch_execz .LBB0_1203
	s_waitcnt lgkmcnt(0)
	v_add_f32_e32 v18, v16, v17
	v_lshl_add_u64 v[16:17], v[92:93], 2, s[42:43]
	global_atomic_add_f32 v[16:17], v18, off
.LBB0_1203:
	s_or_b64 exec, exec, s[36:37]
	v_lshlrev_b32_e32 v16, 16, v68
	s_waitcnt lgkmcnt(0)
	v_and_b32_e32 v17, 0xffff0000, v68
	v_lshlrev_b32_e32 v18, 16, v69
	v_and_b32_e32 v19, 0xffff0000, v69
	v_lshlrev_b32_e32 v20, 16, v70
	v_and_b32_e32 v21, 0xffff0000, v70
	v_lshlrev_b32_e32 v22, 16, v71
	v_and_b32_e32 v23, 0xffff0000, v71
	v_lshlrev_b32_e32 v28, 16, v66
	v_and_b32_e32 v29, 0xffff0000, v66
	v_lshlrev_b32_e32 v30, 16, v67
	v_and_b32_e32 v31, 0xffff0000, v67
	v_pk_add_f32 v[14:15], v[14:15], v[18:19]
	v_pk_add_f32 v[12:13], v[12:13], v[16:17]
	v_pk_add_f32 v[16:17], v[10:11], v[22:23]
	v_pk_add_f32 v[18:19], v[8:9], v[20:21]
	v_pk_add_f32 v[20:21], v[2:3], v[30:31]
	v_pk_add_f32 v[22:23], v[0:1], v[28:29]
	v_mul_f32_e32 v1, v13, v13
	v_mul_f32_e32 v2, v15, v15
	v_fmac_f32_e32 v1, v12, v12
	v_fmac_f32_e32 v2, v14, v14
	v_lshlrev_b32_e32 v24, 16, v64
	v_and_b32_e32 v25, 0xffff0000, v64
	v_lshlrev_b32_e32 v26, 16, v65
	v_and_b32_e32 v27, 0xffff0000, v65
	v_add_f32_e32 v1, v1, v2
	v_mul_f32_e32 v2, v19, v19
	v_pk_add_f32 v[6:7], v[6:7], v[26:27]
	v_pk_add_f32 v[4:5], v[4:5], v[24:25]
	v_fmac_f32_e32 v2, v18, v18
	v_add_f32_e32 v1, v2, v1
	v_mul_f32_e32 v2, v5, v5
	v_mul_f32_e32 v3, v7, v7
	v_mul_f32_e32 v0, v17, v17
	v_fmac_f32_e32 v2, v4, v4
	v_fmac_f32_e32 v3, v6, v6
	v_fmac_f32_e32 v0, v16, v16
	v_add_f32_e32 v2, v2, v3
	v_mul_f32_e32 v3, v23, v23
	v_add_f32_e32 v0, v0, v1
	v_mul_f32_e32 v1, v21, v21
	v_fmac_f32_e32 v3, v22, v22
	v_fmac_f32_e32 v1, v20, v20
	v_add_f32_e32 v2, v3, v2
	v_add_f32_e32 v1, v1, v2
	v_add_f32_e32 v0, v0, v1
	ds_bpermute_b32 v1, v197, v0
	v_lshl_add_u64 v[32:33], s[44:45], 0, v[90:91]
	v_cvt_pk_bf16_f32 v8, v12, v13
	v_lshl_add_u64 v[12:13], v[164:165], 1, v[32:33]
	v_cvt_pk_bf16_f32 v9, v14, v15
	s_waitcnt lgkmcnt(0)
	v_add_f32_e32 v0, v0, v1
	ds_bpermute_b32 v1, v198, v0
	v_cvt_pk_bf16_f32 v10, v18, v19
	v_cvt_pk_bf16_f32 v11, v16, v17
	global_store_dwordx4 v[12:13], v[8:11], off
	v_cvt_pk_bf16_f32 v2, v4, v5
	v_cvt_pk_bf16_f32 v3, v6, v7
	v_cvt_pk_bf16_f32 v4, v22, v23
	v_cvt_pk_bf16_f32 v5, v20, v21
	global_store_dwordx4 v[12:13], v[2:5], off offset:256
	s_and_saveexec_b64 s[36:37], vcc
	s_cbranch_execz .LBB0_1205
	s_waitcnt lgkmcnt(0)
	v_add_f32_e32 v2, v0, v1
	v_lshl_add_u64 v[0:1], v[88:89], 2, s[42:43]
	global_atomic_add_f32 v[0:1], v2, off

; __device__ __forceinline__ unsigned cvt_pk(float lo, float hi) { unsigned r; asm("v_cvt_pk_bf16_f32 %0, %1, %2" : "=v"(r) : "v"(lo), "v"(hi)); return r; }
;     __device__ __forceinline__ void operator()(AccRef acc, const pg8::Unit& u, int wr, int wc, int, int) const {
;     ...
;         for (int ai = 0; ai < 2; ++ai) {
;             f32x4 r0[4][2], r1[4][2];
;             if (xp) {
; #pragma unroll
;                 for (int m = 0; m < 4; ++m) { const int row = u.pm * 256 + ai * 128 + wr * 64 + m * 16 + fr;
;                     const float* rsrc = (row < MP) ? xp + (size_t)row * DM : xs + (size_t)(row - MP) * DM;
; #pragma unroll
;                     for (int bj = 0; bj < 2; ++bj) { const int c0 = u.pn * 256 + bj * 128 + wc * 32 + 8 * fq; r0[m][bj] = *(const f32x4*)(rsrc + c0); r1[m][bj] = *(const f32x4*)(rsrc + c0 + 4); } }
;             } else {
;                 v4u pw[4][2];
; #pragma unroll
;                 for (int m = 0; m < 4; ++m) { const int row = u.pm * 256 + ai * 128 + wr * 64 + m * 16 + fr;
; #pragma unroll
;                     for (int bj = 0; bj < 2; ++bj) pw[m][bj] = *(const v4u*)(RB + (size_t)row * DM + u.pn * 256 + bj * 128 + wc * 32 + 8 * fq); }
; #pragma unroll
;                 for (int m = 0; m < 4; ++m)
; #pragma unroll
;                     for (int bj = 0; bj < 2; ++bj) { const v4u w = pw[m][bj]; r0[m][bj] = (f32x4){bf_lo(w.x), bf_hi(w.x), bf_lo(w.y), bf_hi(w.y)}; r1[m][bj] = (f32x4){bf_lo(w.z), bf_hi(w.z), bf_lo(w.w), bf_hi(w.w)}; }
;             }
;             asm volatile("" ::: "memory");
; #pragma unroll
;             for (int m = 0; m < 4; ++m) {
;                 const int row = u.pm * 256 + ai * 128 + wr * 64 + m * 16 + fr;
;                 float ss = 0.f;
; #pragma unroll
;                 for (int bj = 0; bj < 2; ++bj) {
;                     const int c0 = u.pn * 256 + bj * 128 + wc * 32 + 8 * fq;
;                     const f32x4 o0 = r0[m][bj] + acc[ai][bj][m][0], o1 = r1[m][bj] + acc[ai][bj][m][1];
;                     v4u w; w.x = cvt_pk(o0[0], o0[1]); w.y = cvt_pk(o0[2], o0[3]); w.z = cvt_pk(o1[0], o1[1]); w.w = cvt_pk(o1[2], o1[3]);
;                     *(v4u*)(HB + (size_t)row * DM + c0) = w;
.Lp5b_epi:
	s_mov_b64 s[24:25], s[20:21]
	s_mov_b64 s[26:27], s[22:23]
	s_add_u32 s24, s24, 0x7800000
	s_addc_u32 s25, s25, 0
	s_lshl_b32 s26, s58, 8
	v_mov_b32_e32 v141, v196
	s_add_i32 s26, s26, s35
	s_nop 0
	v_and_or_b32 v140, v141, 15, s26
	s_lshl_b32 s26, s57, 8
	s_ashr_i32 s27, s26, 31
	s_or_b32 s30, s26, s28
	s_lshl_b64 s[26:27], s[26:27], 1
	s_add_u32 s26, s24, s26
	v_ashrrev_i32_e32 v141, 1, v141
	s_addc_u32 s27, s25, s27
	v_and_b32_e32 v150, -8, v141
	s_add_u32 s26, s26, s43
	s_addc_u32 s27, s27, 0
	v_ashrrev_i32_e32 v151, 31, v150
	v_ashrrev_i32_e32 v141, 31, v140
	v_lshl_add_u64 v[142:143], v[150:151], 1, s[26:27]
	v_lshlrev_b64 v[186:187], 11, v[140:141]
	v_lshl_add_u64 v[144:145], v[142:143], 0, v[186:187]
	s_mov_b64 s[60:61], 0x40000
	v_lshl_add_u64 v[246:247], v[144:145], 0, s[60:61]
	global_load_dwordx4 v[146:149], v[144:145], off
	global_load_dwordx4 v[158:161], v[144:145], off offset:256
	global_load_dwordx4 v[230:233], v[246:247], off
	global_load_dwordx4 v[234:237], v[246:247], off offset:256
	v_or_b32_e32 v144, 16, v140
	v_ashrrev_i32_e32 v145, 31, v144
	v_lshlrev_b64 v[188:189], 11, v[144:145]
	v_lshl_add_u64 v[144:145], v[142:143], 0, v[188:189]
	v_lshl_add_u64 v[246:247], v[144:145], 0, s[60:61]
	global_load_dwordx4 v[162:165], v[144:145], off
	global_load_dwordx4 v[166:169], v[144:145], off offset:256
	global_load_dwordx4 v[238:241], v[246:247], off
	global_load_dwordx4 v[242:245], v[246:247], off offset:256
	v_or_b32_e32 v144, 32, v140
	v_ashrrev_i32_e32 v145, 31, v144
	v_lshlrev_b64 v[190:191], 11, v[144:145]
	v_lshl_add_u64 v[144:145], v[142:143], 0, v[190:191]
	global_load_dwordx4 v[170:173], v[144:145], off
	global_load_dwordx4 v[174:177], v[144:145], off offset:256
	v_or_b32_e32 v144, 48, v140
	v_ashrrev_i32_e32 v145, 31, v144
	v_lshlrev_b64 v[144:145], 11, v[144:145]
	v_lshl_add_u64 v[182:183], v[142:143], 0, v[144:145]
	global_load_dwordx4 v[178:181], v[182:183], off
	s_nop 0
	global_load_dwordx4 v[182:185], v[182:183], off offset:256
	v_add_u32_e32 v192, s30, v150
	v_ashrrev_i32_e32 v193, 31, v192
	s_and_b64 vcc, exec, s[6:7]
	s_mov_b64 s[6:7], -1
	s_waitcnt vmcnt(0)
	v_lshlrev_b32_e32 v194, 16, v146
	v_and_b32_e32 v195, 0xffff0000, v146
	v_lshlrev_b32_e32 v202, 16, v148
	v_and_b32_e32 v203, 0xffff0000, v148
	v_lshlrev_b32_e32 v200, 16, v147
	v_and_b32_e32 v201, 0xffff0000, v147
	v_lshlrev_b32_e32 v204, 16, v149
	v_and_b32_e32 v205, 0xffff0000, v149
	v_pk_add_f32 v[124:125], v[124:125], v[194:195]
	v_pk_add_f32 v[120:121], v[120:121], v[202:203]
	v_pk_add_f32 v[126:127], v[126:127], v[200:201]
	v_lshlrev_b32_e32 v206, 16, v158
	v_and_b32_e32 v207, 0xffff0000, v158
	v_lshlrev_b32_e32 v158, 16, v159
	v_and_b32_e32 v159, 0xffff0000, v159
	v_lshlrev_b32_e32 v208, 16, v160
	v_lshlrev_b32_e32 v146, 16, v184
	v_and_b32_e32 v147, 0xffff0000, v184
	v_lshlrev_b32_e32 v150, 16, v185
	v_and_b32_e32 v151, 0xffff0000, v185
	v_lshl_add_u64 v[184:185], s[24:25], 0, v[186:187]
	v_pk_add_f32 v[186:187], v[122:123], v[204:205]
	v_cvt_pk_bf16_f32 v122, v124, v125
	v_cvt_pk_bf16_f32 v124, v120, v121
	v_lshlrev_b64 v[120:121], 1, v[192:193]
	v_and_b32_e32 v209, 0xffff0000, v160
	v_lshlrev_b32_e32 v160, 16, v161
	v_and_b32_e32 v161, 0xffff0000, v161
	v_cvt_pk_bf16_f32 v123, v126, v127
	v_lshl_add_u64 v[126:127], v[184:185], 0, v[120:121]
	v_cvt_pk_bf16_f32 v125, v186, v187
	global_store_dwordx4 v[126:127], v[122:125], off
	v_pk_add_f32 v[118:119], v[118:119], v[158:159]
	v_pk_add_f32 v[116:117], v[116:117], v[206:207]
	v_pk_add_f32 v[122:123], v[110:111], v[160:161]
	v_pk_add_f32 v[110:111], v[108:109], v[208:209]
	v_cvt_pk_bf16_f32 v108, v116, v117
	v_cvt_pk_bf16_f32 v109, v118, v119
	v_lshlrev_b32_e32 v210, 16, v162
	v_and_b32_e32 v211, 0xffff0000, v162
	v_lshlrev_b32_e32 v162, 16, v163
	v_and_b32_e32 v163, 0xffff0000, v163
	v_lshlrev_b32_e32 v212, 16, v164
	v_and_b32_e32 v213, 0xffff0000, v164
	v_lshlrev_b32_e32 v164, 16, v165
	v_and_b32_e32 v165, 0xffff0000, v165
	v_cvt_pk_bf16_f32 v110, v110, v111
	v_cvt_pk_bf16_f32 v111, v122, v123
	global_store_dwordx4 v[126:127], v[108:111], off offset:256
	v_lshlrev_b32_e32 v214, 16, v166
	v_and_b32_e32 v215, 0xffff0000, v166
	v_lshl_add_u64 v[108:109], s[24:25], 0, v[188:189]
	v_lshlrev_b32_e32 v166, 16, v167
	v_and_b32_e32 v167, 0xffff0000, v167
	v_lshlrev_b32_e32 v216, 16, v168
	v_and_b32_e32 v217, 0xffff0000, v168
	v_lshlrev_b32_e32 v168, 16, v169
	v_and_b32_e32 v169, 0xffff0000, v169
	v_pk_add_f32 v[110:111], v[114:115], v[162:163]
	v_pk_add_f32 v[112:113], v[112:113], v[210:211]
	v_pk_add_f32 v[114:115], v[106:107], v[164:165]
	v_pk_add_f32 v[106:107], v[104:105], v[212:213]
	v_cvt_pk_bf16_f32 v104, v112, v113
	v_cvt_pk_bf16_f32 v105, v110, v111
	v_lshl_add_u64 v[108:109], v[108:109], 0, v[120:121]
	v_cvt_pk_bf16_f32 v106, v106, v107
	v_cvt_pk_bf16_f32 v107, v114, v115
	global_store_dwordx4 v[108:109], v[104:107], off
	v_pk_add_f32 v[102:103], v[102:103], v[166:167]
	v_pk_add_f32 v[100:101], v[100:101], v[214:215]
	v_pk_add_f32 v[104:105], v[94:95], v[168:169]
	v_pk_add_f32 v[94:95], v[92:93], v[216:217]
	v_cvt_pk_bf16_f32 v92, v100, v101
	v_cvt_pk_bf16_f32 v93, v102, v103
	v_lshlrev_b32_e32 v218, 16, v170
	v_and_b32_e32 v219, 0xffff0000, v170
	v_lshlrev_b32_e32 v170, 16, v171
	v_and_b32_e32 v171, 0xffff0000, v171
	v_lshlrev_b32_e32 v220, 16, v172
	v_and_b32_e32 v221, 0xffff0000, v172
	v_lshlrev_b32_e32 v172, 16, v173
	v_and_b32_e32 v173, 0xffff0000, v173
	v_cvt_pk_bf16_f32 v94, v94, v95
	v_cvt_pk_bf16_f32 v95, v104, v105
	global_store_dwordx4 v[108:109], v[92:95], off offset:256
	v_lshlrev_b32_e32 v222, 16, v174
	v_and_b32_e32 v223, 0xffff0000, v174
; __device__ __forceinline__ unsigned cvt_pk(float lo, float hi) { unsigned r; asm("v_cvt_pk_bf16_f32 %0, %1, %2" : "=v"(r) : "v"(lo), "v"(hi)); return r; }
;     __device__ __forceinline__ void operator()(AccRef acc, const pg8::Unit& u, int wr, int wc, int, int) const {
;     ...
;         for (int ai = 0; ai < 2; ++ai) {
;             f32x4 r0[4][2], r1[4][2];
;             if (xp) {
; #pragma unroll
;                 for (int m = 0; m < 4; ++m) { const int row = u.pm * 256 + ai * 128 + wr * 64 + m * 16 + fr;
;                     const float* rsrc = (row < MP) ? xp + (size_t)row * DM : xs + (size_t)(row - MP) * DM;
; #pragma unroll
;                     for (int bj = 0; bj < 2; ++bj) { const int c0 = u.pn * 256 + bj * 128 + wc * 32 + 8 * fq; r0[m][bj] = *(const f32x4*)(rsrc + c0); r1[m][bj] = *(const f32x4*)(rsrc + c0 + 4); } }
;             } else {
;                 v4u pw[4][2];
; #pragma unroll
;                 for (int m = 0; m < 4; ++m) { const int row = u.pm * 256 + ai * 128 + wr * 64 + m * 16 + fr;
; #pragma unroll
;                     for (int bj = 0; bj < 2; ++bj) pw[m][bj] = *(const v4u*)(RB + (size_t)row * DM + u.pn * 256 + bj * 128 + wc * 32 + 8 * fq); }
; #pragma unroll
;                 for (int m = 0; m < 4; ++m)
; #pragma unroll
;                     for (int bj = 0; bj < 2; ++bj) { const v4u w = pw[m][bj]; r0[m][bj] = (f32x4){bf_lo(w.x), bf_hi(w.x), bf_lo(w.y), bf_hi(w.y)}; r1[m][bj] = (f32x4){bf_lo(w.z), bf_hi(w.z), bf_lo(w.w), bf_hi(w.w)}; }
;             }
;             asm volatile("" ::: "memory");
; #pragma unroll
;             for (int m = 0; m < 4; ++m) {
;                 const int row = u.pm * 256 + ai * 128 + wr * 64 + m * 16 + fr;
;                 float ss = 0.f;
; #pragma unroll
;                 for (int bj = 0; bj < 2; ++bj) {
;                     const int c0 = u.pn * 256 + bj * 128 + wc * 32 + 8 * fq;
;                     const f32x4 o0 = r0[m][bj] + acc[ai][bj][m][0], o1 = r1[m][bj] + acc[ai][bj][m][1];
;                     v4u w; w.x = cvt_pk(o0[0], o0[1]); w.y = cvt_pk(o0[2], o0[3]); w.z = cvt_pk(o1[0], o1[1]); w.w = cvt_pk(o1[2], o1[3]);
;                     *(v4u*)(HB + (size_t)row * DM + c0) = w;
	v_lshl_add_u64 v[92:93], s[24:25], 0, v[190:191]
	v_lshlrev_b32_e32 v174, 16, v175
	v_and_b32_e32 v175, 0xffff0000, v175
	v_lshlrev_b32_e32 v224, 16, v176
	v_and_b32_e32 v225, 0xffff0000, v176
	v_lshlrev_b32_e32 v176, 16, v177
	v_and_b32_e32 v177, 0xffff0000, v177
	v_pk_add_f32 v[94:95], v[98:99], v[170:171]
	v_pk_add_f32 v[96:97], v[96:97], v[218:219]
	v_pk_add_f32 v[98:99], v[90:91], v[172:173]
	v_pk_add_f32 v[90:91], v[88:89], v[220:221]
	v_cvt_pk_bf16_f32 v88, v96, v97
	v_cvt_pk_bf16_f32 v89, v94, v95
	v_lshl_add_u64 v[92:93], v[92:93], 0, v[120:121]
	v_cvt_pk_bf16_f32 v90, v90, v91
	v_cvt_pk_bf16_f32 v91, v98, v99
	global_store_dwordx4 v[92:93], v[88:91], off
	v_pk_add_f32 v[86:87], v[86:87], v[174:175]
	v_pk_add_f32 v[84:85], v[84:85], v[222:223]
	v_pk_add_f32 v[88:89], v[78:79], v[176:177]
	v_pk_add_f32 v[78:79], v[76:77], v[224:225]
	v_cvt_pk_bf16_f32 v76, v84, v85
	v_cvt_pk_bf16_f32 v77, v86, v87
	v_lshlrev_b32_e32 v226, 16, v178
	v_and_b32_e32 v227, 0xffff0000, v178
	v_lshlrev_b32_e32 v178, 16, v179
	v_and_b32_e32 v179, 0xffff0000, v179
	v_lshlrev_b32_e32 v228, 16, v180
	v_and_b32_e32 v229, 0xffff0000, v180
	v_lshlrev_b32_e32 v180, 16, v181
	v_and_b32_e32 v181, 0xffff0000, v181
	v_cvt_pk_bf16_f32 v78, v78, v79
	v_cvt_pk_bf16_f32 v79, v88, v89
	global_store_dwordx4 v[92:93], v[76:79], off offset:256
	v_lshlrev_b32_e32 v148, 16, v182
	v_and_b32_e32 v149, 0xffff0000, v182
	v_lshl_add_u64 v[76:77], s[24:25], 0, v[144:145]
	v_pk_add_f32 v[78:79], v[82:83], v[178:179]
	v_pk_add_f32 v[80:81], v[80:81], v[226:227]
	v_pk_add_f32 v[82:83], v[74:75], v[180:181]
	v_pk_add_f32 v[74:75], v[72:73], v[228:229]
	v_cvt_pk_bf16_f32 v72, v80, v81
	v_cvt_pk_bf16_f32 v73, v78, v79
	v_lshl_add_u64 v[76:77], v[76:77], 0, v[120:121]
	v_lshlrev_b32_e32 v182, 16, v183
	v_and_b32_e32 v183, 0xffff0000, v183
	v_cvt_pk_bf16_f32 v74, v74, v75
	v_cvt_pk_bf16_f32 v75, v82, v83
	global_store_dwordx4 v[76:77], v[72:75], off
	v_pk_add_f32 v[68:69], v[68:69], v[148:149]
	v_pk_add_f32 v[70:71], v[70:71], v[182:183]
	v_pk_add_f32 v[72:73], v[66:67], v[150:151]
	v_pk_add_f32 v[66:67], v[64:65], v[146:147]
	v_cvt_pk_bf16_f32 v64, v68, v69
	v_cvt_pk_bf16_f32 v65, v70, v71
	s_nop 0
	v_cvt_pk_bf16_f32 v66, v66, v67
	v_cvt_pk_bf16_f32 v67, v72, v73
	global_store_dwordx4 v[76:77], v[64:67], off offset:256
	s_nop 1
	v_add_u32_e32 v64, 0x80, v140
	v_ashrrev_i32_e32 v65, 31, v64
	v_lshlrev_b64 v[98:99], 11, v[64:65]
	v_lshl_add_u64 v[64:65], v[142:143], 0, v[98:99]
	v_mov_b64_e32 v[66:67], v[230:231]
	v_mov_b64_e32 v[68:69], v[232:233]
	v_mov_b64_e32 v[70:71], v[234:235]
	v_mov_b64_e32 v[72:73], v[236:237]
	v_add_u32_e32 v64, 0x90, v140
	v_ashrrev_i32_e32 v65, 31, v64
	v_lshlrev_b64 v[100:101], 11, v[64:65]
	v_lshl_add_u64 v[64:65], v[142:143], 0, v[100:101]
	v_mov_b64_e32 v[74:75], v[238:239]
	v_mov_b64_e32 v[76:77], v[240:241]
	v_mov_b64_e32 v[78:79], v[242:243]
	v_mov_b64_e32 v[80:81], v[244:245]
	v_add_u32_e32 v64, 0xa0, v140
	v_ashrrev_i32_e32 v65, 31, v64
	v_lshlrev_b64 v[102:103], 11, v[64:65]
	v_lshl_add_u64 v[64:65], v[142:143], 0, v[102:103]
	global_load_dwordx4 v[82:85], v[64:65], off
	global_load_dwordx4 v[86:89], v[64:65], off offset:256
	v_add_u32_e32 v64, 0xb0, v140
	v_ashrrev_i32_e32 v65, 31, v64
	v_lshlrev_b64 v[64:65], 11, v[64:65]
	v_lshl_add_u64 v[94:95], v[142:143], 0, v[64:65]
	global_load_dwordx4 v[90:93], v[94:95], off
	s_nop 0
	global_load_dwordx4 v[94:97], v[94:95], off offset:256
	v_lshl_add_u64 v[98:99], s[24:25], 0, v[98:99]
	v_lshlrev_b32_e32 v104, 16, v66
	v_and_b32_e32 v105, 0xffff0000, v66
	v_lshlrev_b32_e32 v106, 16, v67
	v_and_b32_e32 v107, 0xffff0000, v67
	v_lshlrev_b32_e32 v108, 16, v68
	v_and_b32_e32 v109, 0xffff0000, v68
	v_lshlrev_b32_e32 v110, 16, v69
	v_and_b32_e32 v111, 0xffff0000, v69
	v_pk_add_f32 v[60:61], v[60:61], v[104:105]
	v_lshlrev_b32_e32 v112, 16, v70
	v_and_b32_e32 v113, 0xffff0000, v70
	v_lshlrev_b32_e32 v70, 16, v71
	v_and_b32_e32 v71, 0xffff0000, v71
	v_lshlrev_b32_e32 v114, 16, v72
	v_and_b32_e32 v115, 0xffff0000, v72
	v_lshlrev_b32_e32 v72, 16, v73
	v_and_b32_e32 v73, 0xffff0000, v73
	v_pk_add_f32 v[62:63], v[62:63], v[106:107]
	v_pk_add_f32 v[104:105], v[58:59], v[110:111]
	v_pk_add_f32 v[58:59], v[56:57], v[108:109]
	v_cvt_pk_bf16_f32 v56, v60, v61
	v_cvt_pk_bf16_f32 v57, v62, v63
	v_lshl_add_u64 v[60:61], v[98:99], 0, v[120:121]
	v_cvt_pk_bf16_f32 v58, v58, v59
	v_cvt_pk_bf16_f32 v59, v104, v105
	global_store_dwordx4 v[60:61], v[56:59], off
	v_pk_add_f32 v[54:55], v[54:55], v[70:71]
	v_pk_add_f32 v[52:53], v[52:53], v[112:113]
	v_pk_add_f32 v[56:57], v[46:47], v[72:73]
	v_pk_add_f32 v[46:47], v[44:45], v[114:115]
	v_cvt_pk_bf16_f32 v44, v52, v53
	v_cvt_pk_bf16_f32 v45, v54, v55
	v_lshlrev_b32_e32 v116, 16, v74
	v_and_b32_e32 v117, 0xffff0000, v74
	v_lshlrev_b32_e32 v74, 16, v75
	v_and_b32_e32 v75, 0xffff0000, v75
	v_lshlrev_b32_e32 v118, 16, v76
	v_and_b32_e32 v119, 0xffff0000, v76
	v_lshlrev_b32_e32 v76, 16, v77
	v_and_b32_e32 v77, 0xffff0000, v77
	v_cvt_pk_bf16_f32 v46, v46, v47
	v_cvt_pk_bf16_f32 v47, v56, v57
	global_store_dwordx4 v[60:61], v[44:47], off offset:256
	v_lshlrev_b32_e32 v122, 16, v78
	v_and_b32_e32 v123, 0xffff0000, v78
	v_lshl_add_u64 v[44:45], s[24:25], 0, v[100:101]
	v_lshlrev_b32_e32 v78, 16, v79
	v_and_b32_e32 v79, 0xffff0000, v79
	v_lshlrev_b32_e32 v124, 16, v80
	v_and_b32_e32 v125, 0xffff0000, v80
	v_lshlrev_b32_e32 v80, 16, v81
	v_and_b32_e32 v81, 0xffff0000, v81
	v_pk_add_f32 v[46:47], v[50:51], v[74:75]
	v_pk_add_f32 v[48:49], v[48:49], v[116:117]
	v_pk_add_f32 v[50:51], v[42:43], v[76:77]
	v_pk_add_f32 v[42:43], v[40:41], v[118:119]
	v_cvt_pk_bf16_f32 v40, v48, v49
	v_cvt_pk_bf16_f32 v41, v46, v47
	v_lshl_add_u64 v[44:45], v[44:45], 0, v[120:121]
	v_cvt_pk_bf16_f32 v42, v42, v43
	v_cvt_pk_bf16_f32 v43, v50, v51
	global_store_dwordx4 v[44:45], v[40:43], off
	v_pk_add_f32 v[38:39], v[38:39], v[78:79]
	v_pk_add_f32 v[36:37], v[36:37], v[122:123]
	v_pk_add_f32 v[40:41], v[30:31], v[80:81]
	v_pk_add_f32 v[30:31], v[28:29], v[124:125]
	v_cvt_pk_bf16_f32 v28, v36, v37
	v_cvt_pk_bf16_f32 v29, v38, v39
	s_waitcnt vmcnt(6)
; __device__ __forceinline__ unsigned cvt_pk(float lo, float hi) { unsigned r; asm("v_cvt_pk_bf16_f32 %0, %1, %2" : "=v"(r) : "v"(lo), "v"(hi)); return r; }
; #define PG8_BAR __builtin_amdgcn_s_barrier()
; template <int KK, class Epi, class Sched, bool ALIGN_EPI = true>
; __device__ __forceinline__ void gemm_phase(LAS unsigned char* lds, const bf16* gA, const bf16* gBt, const Sched& S, const Epi& E, const int wid) {
;     ...
;         if constexpr (ALIGN_EPI) { if (wr == 0) PG8_BAR; }
;         E(acc, cur, wr, wc, fr, fq);
;         if (!has_next) break;
; #pragma unroll
;         for (int a = 0; a < 2; ++a)
; #pragma unroll
;             for (int b = 0; b < 2; ++b)
; #pragma unroll
;                 for (int m = 0; m < 4; ++m)
; #pragma unroll
;                     for (int n = 0; n < 2; ++n) acc[a][b][m][n] = (f32x4){0.f, 0.f, 0.f, 0.f};
;         cur = nxt; cA = nA; cB = nB; ++ui;
;         if constexpr (ALIGN_EPI) { if (wr == 1) PG8_BAR; }
;     __device__ __forceinline__ void operator()(AccRef acc, const pg8::Unit& u, int wr, int wc, int, int) const {
;     ...
;             for (int m = 0; m < 4; ++m) {
;                 const int row = u.pm * 256 + ai * 128 + wr * 64 + m * 16 + fr;
;                 float ss = 0.f;
; #pragma unroll
;                 for (int bj = 0; bj < 2; ++bj) {
;                     const int c0 = u.pn * 256 + bj * 128 + wc * 32 + 8 * fq;
;                     const f32x4 o0 = r0[m][bj] + acc[ai][bj][m][0], o1 = r1[m][bj] + acc[ai][bj][m][1];
;                     v4u w; w.x = cvt_pk(o0[0], o0[1]); w.y = cvt_pk(o0[2], o0[3]); w.z = cvt_pk(o1[0], o1[1]); w.w = cvt_pk(o1[2], o1[3]);
;                     *(v4u*)(HB + (size_t)row * DM + c0) = w;
;                     ss += (o0[0] * o0[0] + o0[1] * o0[1]) + (o0[2] * o0[2] + o0[3] * o0[3]) + (o1[0] * o1[0] + o1[1] * o1[1]) + (o1[2] * o1[2] + o1[3] * o1[3]);
;                 }
	v_lshlrev_b32_e32 v126, 16, v82
	v_and_b32_e32 v127, 0xffff0000, v82
	v_lshlrev_b32_e32 v82, 16, v83
	v_and_b32_e32 v83, 0xffff0000, v83
	v_lshlrev_b32_e32 v140, 16, v84
	v_and_b32_e32 v141, 0xffff0000, v84
	v_lshlrev_b32_e32 v84, 16, v85
	v_and_b32_e32 v85, 0xffff0000, v85
	v_cvt_pk_bf16_f32 v30, v30, v31
	v_cvt_pk_bf16_f32 v31, v40, v41
	global_store_dwordx4 v[44:45], v[28:31], off offset:256
	s_waitcnt vmcnt(6)
	v_lshlrev_b32_e32 v142, 16, v86
	v_and_b32_e32 v143, 0xffff0000, v86
	v_lshl_add_u64 v[28:29], s[24:25], 0, v[102:103]
	v_lshlrev_b32_e32 v86, 16, v87
	v_and_b32_e32 v87, 0xffff0000, v87
	v_lshlrev_b32_e32 v144, 16, v88
	v_and_b32_e32 v145, 0xffff0000, v88
	v_lshlrev_b32_e32 v88, 16, v89
	v_and_b32_e32 v89, 0xffff0000, v89
	v_pk_add_f32 v[30:31], v[34:35], v[82:83]
	v_pk_add_f32 v[32:33], v[32:33], v[126:127]
	v_pk_add_f32 v[34:35], v[26:27], v[84:85]
	v_pk_add_f32 v[26:27], v[24:25], v[140:141]
	v_cvt_pk_bf16_f32 v24, v32, v33
	v_cvt_pk_bf16_f32 v25, v30, v31
	v_lshl_add_u64 v[28:29], v[28:29], 0, v[120:121]
	v_cvt_pk_bf16_f32 v26, v26, v27
	v_cvt_pk_bf16_f32 v27, v34, v35
	global_store_dwordx4 v[28:29], v[24:27], off
	v_pk_add_f32 v[22:23], v[22:23], v[86:87]
	v_pk_add_f32 v[20:21], v[20:21], v[142:143]
	v_pk_add_f32 v[24:25], v[14:15], v[88:89]
	v_pk_add_f32 v[14:15], v[12:13], v[144:145]
	v_cvt_pk_bf16_f32 v12, v20, v21
	v_cvt_pk_bf16_f32 v13, v22, v23
	s_waitcnt vmcnt(6)
	v_lshlrev_b32_e32 v146, 16, v90
	v_and_b32_e32 v147, 0xffff0000, v90
	v_lshlrev_b32_e32 v90, 16, v91
	v_and_b32_e32 v91, 0xffff0000, v91
	v_lshlrev_b32_e32 v148, 16, v92
	v_and_b32_e32 v149, 0xffff0000, v92
	v_lshlrev_b32_e32 v92, 16, v93
	v_and_b32_e32 v93, 0xffff0000, v93
	v_cvt_pk_bf16_f32 v14, v14, v15
	v_cvt_pk_bf16_f32 v15, v24, v25
	global_store_dwordx4 v[28:29], v[12:15], off offset:256
	s_waitcnt vmcnt(6)
	v_lshlrev_b32_e32 v66, 16, v96
	v_and_b32_e32 v67, 0xffff0000, v96
	v_lshl_add_u64 v[12:13], s[24:25], 0, v[64:65]
	v_lshlrev_b32_e32 v96, 16, v97
	v_and_b32_e32 v97, 0xffff0000, v97
	v_pk_add_f32 v[14:15], v[18:19], v[90:91]
	v_pk_add_f32 v[16:17], v[16:17], v[146:147]
	v_pk_add_f32 v[18:19], v[10:11], v[92:93]
	v_pk_add_f32 v[10:11], v[8:9], v[148:149]
	v_cvt_pk_bf16_f32 v8, v16, v17
	v_cvt_pk_bf16_f32 v9, v14, v15
	v_lshl_add_u64 v[12:13], v[12:13], 0, v[120:121]
	v_lshlrev_b32_e32 v68, 16, v94
	v_and_b32_e32 v69, 0xffff0000, v94
	v_lshlrev_b32_e32 v94, 16, v95
	v_and_b32_e32 v95, 0xffff0000, v95
	v_cvt_pk_bf16_f32 v10, v10, v11
	v_cvt_pk_bf16_f32 v11, v18, v19
	global_store_dwordx4 v[12:13], v[8:11], off
	v_pk_add_f32 v[6:7], v[6:7], v[94:95]
	v_pk_add_f32 v[4:5], v[4:5], v[68:69]
	v_pk_add_f32 v[8:9], v[2:3], v[96:97]
	v_pk_add_f32 v[2:3], v[0:1], v[66:67]
	v_cvt_pk_bf16_f32 v0, v4, v5
	v_cvt_pk_bf16_f32 v1, v6, v7
	s_nop 0
	v_cvt_pk_bf16_f32 v2, v2, v3
	v_cvt_pk_bf16_f32 v3, v8, v9
	global_store_dwordx4 v[12:13], v[0:3], off offset:256
	s_cbranch_vccnz .LBB0_1283
	s_andn2_b64 vcc, exec, s[10:11]
	s_cbranch_vccnz .LBB0_1282
	s_barrier
	s_branch .LBB0_1282
